# back-edge rotation: the next-tile pointer select block moved from the head of each GEMM loop iteration to the end of the previous iteration's last compute segment
# baseline (speedup 1.0000x reference)
; #define G_STAGE(bufoff, gbase) do { _Pragma("unroll") for (int _i = 0; _i < 2; ++_i) \
;         __builtin_amdgcn_global_load_lds((const unsigned*)((const char*)(gbase) + voff[_i]), (LAS unsigned*)(lds + (bufoff) + ldsw + _i * 8192), 16, 0, 0); } while (0)
; #define G_LDA(dst, b, h) do { _Pragma("unroll") for (int m = 0; m < 4; ++m) _Pragma("unroll") for (int k = 0; k < 2; ++k) dst[m][k] = *(const LAS bf16x8*)(lds + G_SA(b, h) + aoff + m * 2048 + k * 1024); } while (0)
; #define G_LDB(dst, b, h) do { _Pragma("unroll") for (int n = 0; n < 2; ++n) _Pragma("unroll") for (int k = 0; k < 2; ++k) dst[n][k] = *(const LAS bf16x8*)(lds + G_SB(b, h) + boff + n * 2048 + k * 1024); } while (0)
; #define G_MMA(ai, bj, At, Bt) do { __builtin_amdgcn_s_setprio(1); _Pragma("unroll") for (int m = 0; m < 4; ++m) _Pragma("unroll") for (int n = 0; n < 2; ++n) _Pragma("unroll") for (int k = 0; k < 2; ++k) \
;         acc[ai][bj][m][n] = MFMA16(Bt[n][k], At[m][k], acc[ai][bj][m][n]); __builtin_amdgcn_s_setprio(0); } while (0)
; #define G_WAIT_V(n) asm volatile("s_waitcnt vmcnt(" #n ")" ::: "memory")
; #define G_WAIT_L(n) asm volatile("s_waitcnt lgkmcnt(" #n ")" ::: "memory")
; #define G_BAR __builtin_amdgcn_s_barrier()
; #define G_SCHED __builtin_amdgcn_sched_barrier(0)
; template <class Epi>
; __device__ __forceinline__ void gemm_phase(LAS unsigned char* lds, const bf16_t* Ag, const bf16_t* Btg, const int K, const int nM, const int nN, const Epi& E) {
;     ...
;             G_LDB(B0, 0, 0); G_SCHED; G_LDA(At, 0, 0); G_STAGE(G_SA(1, 1), a1 + hstep);
;             G_WAIT_L(8); G_BAR; G_WAIT_L(0); G_MMA(0, 0, At, B0); G_BAR; G_SCHED;
;             G_LDB(B1, 0, 1); G_STAGE(G_SB(0, 0), b2);
;             G_BAR; G_WAIT_L(0); G_MMA(0, 1, At, B1); G_BAR;
;             G_LDA(At, 0, 1); G_STAGE(G_SA(0, 0), a2);
;             G_BAR; G_WAIT_L(0); G_MMA(1, 0, At, B0); G_BAR; G_SCHED;
;             G_STAGE(G_SB(0, 1), b2 + hstep);
;             G_WAIT_V(6); G_BAR; G_MMA(1, 1, At, B1); G_BAR;
.LmainW_78:
	ds_read_b128 v[124:127], v217
	ds_read_b128 v[128:131], v217 offset:1024
	ds_read_b128 v[132:135], v217 offset:2048
	ds_read_b128 v[136:139], v217 offset:3072
	s_add_i32 m0, s58, 0xc000
	ds_read_b128 v[140:143], v186
	ds_read_b128 v[148:151], v186 offset:1024
	ds_read_b128 v[152:155], v186 offset:2048
	ds_read_b128 v[156:159], v186 offset:3072
	ds_read_b128 v[188:191], v186 offset:4096
	ds_read_b128 v[192:195], v186 offset:5120
	ds_read_b128 v[222:225], v186 offset:6144
	global_load_lds_dwordx4 v170, s[50:51]
	s_add_i32 m0, s58, 0xe000
	ds_read_b128 v[226:229], v186 offset:7168
	global_load_lds_dwordx4 v168, s[50:51]
	s_waitcnt lgkmcnt(8)
	s_barrier
	s_waitcnt lgkmcnt(0)
	s_setprio 1
	s_waitcnt lgkmcnt(0)
	v_mfma_f32_16x16x32_bf16 v[164:167], v[124:127], v[140:143], v[164:167]
	v_mfma_f32_16x16x32_bf16 v[160:163], v[132:135], v[140:143], v[160:163]
	v_mfma_f32_16x16x32_bf16 v[116:119], v[124:127], v[152:155], v[116:119]
	v_mfma_f32_16x16x32_bf16 v[112:115], v[132:135], v[152:155], v[112:115]
	v_mfma_f32_16x16x32_bf16 v[100:103], v[124:127], v[188:191], v[100:103]
	v_mfma_f32_16x16x32_bf16 v[96:99], v[132:135], v[188:191], v[96:99]
	v_mfma_f32_16x16x32_bf16 v[84:87], v[124:127], v[222:225], v[84:87]
	v_mfma_f32_16x16x32_bf16 v[80:83], v[132:135], v[222:225], v[80:83]
	v_mfma_f32_16x16x32_bf16 v[164:167], v[128:131], v[148:151], v[164:167]
	v_mfma_f32_16x16x32_bf16 v[160:163], v[136:139], v[148:151], v[160:163]
	v_mfma_f32_16x16x32_bf16 v[116:119], v[128:131], v[156:159], v[116:119]
	v_mfma_f32_16x16x32_bf16 v[112:115], v[136:139], v[156:159], v[112:115]
	v_mfma_f32_16x16x32_bf16 v[100:103], v[128:131], v[192:195], v[100:103]
	v_mfma_f32_16x16x32_bf16 v[96:99], v[136:139], v[192:195], v[96:99]
	v_mfma_f32_16x16x32_bf16 v[84:87], v[128:131], v[226:229], v[84:87]
	v_mfma_f32_16x16x32_bf16 v[80:83], v[136:139], v[226:229], v[80:83]
	s_setprio 0
	s_barrier
	ds_read_b128 v[230:233], v217 offset:16384
	ds_read_b128 v[234:237], v217 offset:17408
	s_add_i32 m0, s57, 0x10000
	ds_read_b128 v[238:241], v217 offset:18432
	global_load_lds_dwordx4 v0, s[52:53]
	s_add_i32 m0, s57, 0x12000
	ds_read_b128 v[242:245], v217 offset:19456
	global_load_lds_dwordx4 v2, s[52:53]
	s_barrier
	s_waitcnt lgkmcnt(0)
	s_setprio 1
	s_waitcnt lgkmcnt(0)
	v_mfma_f32_16x16x32_bf16 v[144:147], v[230:233], v[140:143], v[144:147]
	v_mfma_f32_16x16x32_bf16 v[120:123], v[238:241], v[140:143], v[120:123]
	v_mfma_f32_16x16x32_bf16 v[108:111], v[230:233], v[152:155], v[108:111]
	v_mfma_f32_16x16x32_bf16 v[104:107], v[238:241], v[152:155], v[104:107]
	v_mfma_f32_16x16x32_bf16 v[92:95], v[230:233], v[188:191], v[92:95]
	v_mfma_f32_16x16x32_bf16 v[88:91], v[238:241], v[188:191], v[88:91]
	v_mfma_f32_16x16x32_bf16 v[76:79], v[230:233], v[222:225], v[76:79]
	v_mfma_f32_16x16x32_bf16 v[72:75], v[238:241], v[222:225], v[72:75]
	v_mfma_f32_16x16x32_bf16 v[144:147], v[234:237], v[148:151], v[144:147]
	v_mfma_f32_16x16x32_bf16 v[120:123], v[242:245], v[148:151], v[120:123]
	v_mfma_f32_16x16x32_bf16 v[108:111], v[234:237], v[156:159], v[108:111]
	v_mfma_f32_16x16x32_bf16 v[104:107], v[242:245], v[156:159], v[104:107]
	v_mfma_f32_16x16x32_bf16 v[92:95], v[234:237], v[192:195], v[92:95]
	v_mfma_f32_16x16x32_bf16 v[88:91], v[242:245], v[192:195], v[88:91]
	v_mfma_f32_16x16x32_bf16 v[76:79], v[234:237], v[226:229], v[76:79]
	v_mfma_f32_16x16x32_bf16 v[72:75], v[242:245], v[226:229], v[72:75]
	s_setprio 0
	s_mov_b32 m0, s58
	s_barrier
	ds_read_b128 v[140:143], v186 offset:16384
	ds_read_b128 v[148:151], v186 offset:17408
	ds_read_b128 v[152:155], v186 offset:18432
	ds_read_b128 v[156:159], v186 offset:19456
	ds_read_b128 v[188:191], v186 offset:20480
	ds_read_b128 v[192:195], v186 offset:21504
	ds_read_b128 v[222:225], v186 offset:22528
	global_load_lds_dwordx4 v0, s[54:55]
	s_mov_b32 m0, s59
	ds_read_b128 v[226:229], v186 offset:23552
	global_load_lds_dwordx4 v2, s[54:55]
	s_barrier
	s_waitcnt lgkmcnt(0)
	s_setprio 1
	s_waitcnt lgkmcnt(0)
	v_mfma_f32_16x16x32_bf16 v[60:63], v[124:127], v[140:143], v[60:63]
	v_mfma_f32_16x16x32_bf16 v[56:59], v[132:135], v[140:143], v[56:59]
	v_mfma_f32_16x16x32_bf16 v[44:47], v[124:127], v[152:155], v[44:47]
	v_mfma_f32_16x16x32_bf16 v[40:43], v[132:135], v[152:155], v[40:43]
	v_mfma_f32_16x16x32_bf16 v[28:31], v[124:127], v[188:191], v[28:31]
	v_mfma_f32_16x16x32_bf16 v[24:27], v[132:135], v[188:191], v[24:27]
	v_mfma_f32_16x16x32_bf16 v[12:15], v[124:127], v[222:225], v[12:15]
	v_mfma_f32_16x16x32_bf16 v[8:11], v[132:135], v[222:225], v[8:11]
	v_mfma_f32_16x16x32_bf16 v[60:63], v[128:131], v[148:151], v[60:63]
	v_mfma_f32_16x16x32_bf16 v[56:59], v[136:139], v[148:151], v[56:59]
	v_mfma_f32_16x16x32_bf16 v[44:47], v[128:131], v[156:159], v[44:47]
	v_mfma_f32_16x16x32_bf16 v[40:43], v[136:139], v[156:159], v[40:43]
	v_mfma_f32_16x16x32_bf16 v[28:31], v[128:131], v[192:195], v[28:31]
	v_mfma_f32_16x16x32_bf16 v[24:27], v[136:139], v[192:195], v[24:27]
	v_mfma_f32_16x16x32_bf16 v[12:15], v[128:131], v[226:229], v[12:15]
	v_mfma_f32_16x16x32_bf16 v[8:11], v[136:139], v[226:229], v[8:11]
	s_setprio 0
	s_barrier
	s_add_u32 s74, s52, 0x40000
	s_addc_u32 s75, s53, 0
	s_add_i32 m0, s57, 0x14000
	s_nop 0
	global_load_lds_dwordx4 v0, s[74:75]
	s_add_i32 m0, s57, 0x16000
	s_nop 0
	global_load_lds_dwordx4 v2, s[74:75]
	s_waitcnt vmcnt(6)
	s_barrier
; #define G_STAGE(bufoff, gbase) do { _Pragma("unroll") for (int _i = 0; _i < 2; ++_i) \
;         __builtin_amdgcn_global_load_lds((const unsigned*)((const char*)(gbase) + voff[_i]), (LAS unsigned*)(lds + (bufoff) + ldsw + _i * 8192), 16, 0, 0); } while (0)
; #define G_LDA(dst, b, h) do { _Pragma("unroll") for (int m = 0; m < 4; ++m) _Pragma("unroll") for (int k = 0; k < 2; ++k) dst[m][k] = *(const LAS bf16x8*)(lds + G_SA(b, h) + aoff + m * 2048 + k * 1024); } while (0)
; #define G_LDB(dst, b, h) do { _Pragma("unroll") for (int n = 0; n < 2; ++n) _Pragma("unroll") for (int k = 0; k < 2; ++k) dst[n][k] = *(const LAS bf16x8*)(lds + G_SB(b, h) + boff + n * 2048 + k * 1024); } while (0)
; #define G_MMA(ai, bj, At, Bt) do { __builtin_amdgcn_s_setprio(1); _Pragma("unroll") for (int m = 0; m < 4; ++m) _Pragma("unroll") for (int n = 0; n < 2; ++n) _Pragma("unroll") for (int k = 0; k < 2; ++k) \
;         acc[ai][bj][m][n] = MFMA16(Bt[n][k], At[m][k], acc[ai][bj][m][n]); __builtin_amdgcn_s_setprio(0); } while (0)
; #define G_WAIT_V(n) asm volatile("s_waitcnt vmcnt(" #n ")" ::: "memory")
; #define G_WAIT_L(n) asm volatile("s_waitcnt lgkmcnt(" #n ")" ::: "memory")
; #define G_BAR __builtin_amdgcn_s_barrier()
; #define G_SCHED __builtin_amdgcn_sched_barrier(0)
; template <class Epi>
; __device__ __forceinline__ void gemm_phase(LAS unsigned char* lds, const bf16_t* Ag, const bf16_t* Btg, const int K, const int nM, const int nN, const Epi& E) {
;     ...
;             G_WAIT_V(6); G_BAR; G_MMA(1, 1, At, B1); G_BAR;
;             G_LDB(B0, 1, 0); G_SCHED; G_LDA(At, 1, 0); G_STAGE(G_SA(0, 1), a2 + hstep);
;             G_WAIT_L(8); G_BAR; G_WAIT_L(0); G_MMA(0, 0, At, B0); G_BAR; G_SCHED;
;             G_LDB(B1, 1, 1); G_STAGE(G_SB(1, 0), b3);
;             G_BAR; G_WAIT_L(0); G_MMA(0, 1, At, B1); G_BAR;
	s_setprio 1
	v_mfma_f32_16x16x32_bf16 v[68:71], v[230:233], v[140:143], v[68:71]
	v_mfma_f32_16x16x32_bf16 v[64:67], v[238:241], v[140:143], v[64:67]
	v_mfma_f32_16x16x32_bf16 v[52:55], v[230:233], v[152:155], v[52:55]
	v_mfma_f32_16x16x32_bf16 v[48:51], v[238:241], v[152:155], v[48:51]
	v_mfma_f32_16x16x32_bf16 v[36:39], v[230:233], v[188:191], v[36:39]
	v_mfma_f32_16x16x32_bf16 v[32:35], v[238:241], v[188:191], v[32:35]
	v_mfma_f32_16x16x32_bf16 v[20:23], v[230:233], v[222:225], v[20:23]
	v_mfma_f32_16x16x32_bf16 v[16:19], v[238:241], v[222:225], v[16:19]
	v_mfma_f32_16x16x32_bf16 v[68:71], v[234:237], v[148:151], v[68:71]
	v_mfma_f32_16x16x32_bf16 v[64:67], v[242:245], v[148:151], v[64:67]
	v_mfma_f32_16x16x32_bf16 v[52:55], v[234:237], v[156:159], v[52:55]
	v_mfma_f32_16x16x32_bf16 v[48:51], v[242:245], v[156:159], v[48:51]
	v_mfma_f32_16x16x32_bf16 v[36:39], v[234:237], v[192:195], v[36:39]
	v_mfma_f32_16x16x32_bf16 v[32:35], v[242:245], v[192:195], v[32:35]
	v_mfma_f32_16x16x32_bf16 v[20:23], v[234:237], v[226:229], v[20:23]
	v_mfma_f32_16x16x32_bf16 v[16:19], v[242:245], v[226:229], v[16:19]
	s_setprio 0
	s_barrier
	ds_read_b128 v[124:127], v217 offset:32768
	ds_read_b128 v[128:131], v217 offset:33792
	ds_read_b128 v[132:135], v217 offset:34816
	ds_read_b128 v[136:139], v217 offset:35840
	s_add_u32 s54, s54, 0x40000
	s_addc_u32 s55, s55, 0
	s_mov_b32 m0, s60
	ds_read_b128 v[140:143], v186 offset:32768
	ds_read_b128 v[148:151], v186 offset:33792
	ds_read_b128 v[152:155], v186 offset:34816
	ds_read_b128 v[156:159], v186 offset:35840
	ds_read_b128 v[188:191], v186 offset:36864
	ds_read_b128 v[192:195], v186 offset:37888
	ds_read_b128 v[222:225], v186 offset:38912
	global_load_lds_dwordx4 v0, s[54:55]
	s_mov_b32 m0, s61
	ds_read_b128 v[226:229], v186 offset:39936
	global_load_lds_dwordx4 v2, s[54:55]
	s_waitcnt lgkmcnt(8)
	s_barrier
	s_waitcnt lgkmcnt(0)
	s_setprio 1
	s_waitcnt lgkmcnt(0)
	v_mfma_f32_16x16x32_bf16 v[164:167], v[124:127], v[140:143], v[164:167]
	v_mfma_f32_16x16x32_bf16 v[160:163], v[132:135], v[140:143], v[160:163]
	v_mfma_f32_16x16x32_bf16 v[116:119], v[124:127], v[152:155], v[116:119]
	v_mfma_f32_16x16x32_bf16 v[112:115], v[132:135], v[152:155], v[112:115]
	v_mfma_f32_16x16x32_bf16 v[100:103], v[124:127], v[188:191], v[100:103]
	v_mfma_f32_16x16x32_bf16 v[96:99], v[132:135], v[188:191], v[96:99]
	v_mfma_f32_16x16x32_bf16 v[84:87], v[124:127], v[222:225], v[84:87]
	v_mfma_f32_16x16x32_bf16 v[80:83], v[132:135], v[222:225], v[80:83]
	v_mfma_f32_16x16x32_bf16 v[164:167], v[128:131], v[148:151], v[164:167]
	v_mfma_f32_16x16x32_bf16 v[160:163], v[136:139], v[148:151], v[160:163]
	v_mfma_f32_16x16x32_bf16 v[116:119], v[128:131], v[156:159], v[116:119]
	v_mfma_f32_16x16x32_bf16 v[112:115], v[136:139], v[156:159], v[112:115]
	v_mfma_f32_16x16x32_bf16 v[100:103], v[128:131], v[192:195], v[100:103]
	v_mfma_f32_16x16x32_bf16 v[96:99], v[136:139], v[192:195], v[96:99]
	v_mfma_f32_16x16x32_bf16 v[84:87], v[128:131], v[226:229], v[84:87]
	v_mfma_f32_16x16x32_bf16 v[80:83], v[136:139], v[226:229], v[80:83]
	s_setprio 0
	s_barrier
	s_add_i32 s26, 0, 0x1c000
	s_add_i32 m0, s57, 0x18000
	ds_read_b128 v[230:233], v217 offset:49152
	ds_read_b128 v[234:237], v217 offset:50176
	ds_read_b128 v[238:241], v217 offset:51200
	ds_read_b128 v[242:245], v217 offset:52224
	s_add_u32 s98, s52, 0x80
	s_addc_u32 s99, s53, 0
	global_load_lds_dwordx4 v0, s[98:99]
	s_add_i32 m0, s57, 0x1a000
	s_nop 0
	global_load_lds_dwordx4 v2, s[98:99]
	s_barrier
	s_waitcnt lgkmcnt(0)
	s_setprio 1
	s_waitcnt lgkmcnt(0)
	v_mfma_f32_16x16x32_bf16 v[144:147], v[230:233], v[140:143], v[144:147]
	v_mfma_f32_16x16x32_bf16 v[120:123], v[238:241], v[140:143], v[120:123]
	v_mfma_f32_16x16x32_bf16 v[108:111], v[230:233], v[152:155], v[108:111]
	v_mfma_f32_16x16x32_bf16 v[104:107], v[238:241], v[152:155], v[104:107]
	v_mfma_f32_16x16x32_bf16 v[92:95], v[230:233], v[188:191], v[92:95]
	v_mfma_f32_16x16x32_bf16 v[88:91], v[238:241], v[188:191], v[88:91]
	v_mfma_f32_16x16x32_bf16 v[76:79], v[230:233], v[222:225], v[76:79]
	v_mfma_f32_16x16x32_bf16 v[72:75], v[238:241], v[222:225], v[72:75]
	v_mfma_f32_16x16x32_bf16 v[144:147], v[234:237], v[148:151], v[144:147]
	v_mfma_f32_16x16x32_bf16 v[120:123], v[242:245], v[148:151], v[120:123]
	v_mfma_f32_16x16x32_bf16 v[108:111], v[234:237], v[156:159], v[108:111]
	v_mfma_f32_16x16x32_bf16 v[104:107], v[242:245], v[156:159], v[104:107]
	v_mfma_f32_16x16x32_bf16 v[92:95], v[234:237], v[192:195], v[92:95]
	v_mfma_f32_16x16x32_bf16 v[88:91], v[242:245], v[192:195], v[88:91]
	v_mfma_f32_16x16x32_bf16 v[76:79], v[234:237], v[226:229], v[76:79]
	v_mfma_f32_16x16x32_bf16 v[72:75], v[242:245], v[226:229], v[72:75]
	s_setprio 0
	s_mov_b32 m0, s62
	s_barrier
; #define G_STAGE(bufoff, gbase) do { _Pragma("unroll") for (int _i = 0; _i < 2; ++_i) \
;         __builtin_amdgcn_global_load_lds((const unsigned*)((const char*)(gbase) + voff[_i]), (LAS unsigned*)(lds + (bufoff) + ldsw + _i * 8192), 16, 0, 0); } while (0)
; #define G_LDA(dst, b, h) do { _Pragma("unroll") for (int m = 0; m < 4; ++m) _Pragma("unroll") for (int k = 0; k < 2; ++k) dst[m][k] = *(const LAS bf16x8*)(lds + G_SA(b, h) + aoff + m * 2048 + k * 1024); } while (0)
; #define G_MMA(ai, bj, At, Bt) do { __builtin_amdgcn_s_setprio(1); _Pragma("unroll") for (int m = 0; m < 4; ++m) _Pragma("unroll") for (int n = 0; n < 2; ++n) _Pragma("unroll") for (int k = 0; k < 2; ++k) \
;         acc[ai][bj][m][n] = MFMA16(Bt[n][k], At[m][k], acc[ai][bj][m][n]); __builtin_amdgcn_s_setprio(0); } while (0)
; #define G_WAIT_V(n) asm volatile("s_waitcnt vmcnt(" #n ")" ::: "memory")
; #define G_WAIT_L(n) asm volatile("s_waitcnt lgkmcnt(" #n ")" ::: "memory")
; #define G_BAR __builtin_amdgcn_s_barrier()
; #define G_SCHED __builtin_amdgcn_sched_barrier(0)
; template <class Epi>
; __device__ __forceinline__ void gemm_phase(LAS unsigned char* lds, const bf16_t* Ag, const bf16_t* Btg, const int K, const int nM, const int nN, const Epi& E) {
;     ...
;         for (int t = 0; t < nt; t += 2) {
;             const bool last = (t == nt - 2);
;             const char* a1 = cA + (size_t)(t + 1) * kstep;
;             const char* a2 = last ? nA : cA + (size_t)(t + 2) * kstep; const char* b2 = last ? nB : cB + (size_t)(t + 2) * kstep;
;             const char* a3 = a2 + kstep; const char* b3 = b2 + kstep;
;     ...
;             G_LDA(At, 1, 1); G_STAGE(G_SA(1, 0), a3);
;             G_BAR; G_WAIT_L(0); G_MMA(1, 0, At, B0); G_BAR; G_SCHED;
;             G_STAGE(G_SB(1, 1), b3 + hstep);
;             G_WAIT_V(6); G_BAR; G_MMA(1, 1, At, B1); G_BAR;
	ds_read_b128 v[140:143], v186 offset:49152
	ds_read_b128 v[148:151], v186 offset:50176
	ds_read_b128 v[152:155], v186 offset:51200
	ds_read_b128 v[156:159], v186 offset:52224
	ds_read_b128 v[188:191], v186 offset:53248
	ds_read_b128 v[192:195], v186 offset:54272
	ds_read_b128 v[222:225], v186 offset:55296
	ds_read_b128 v[226:229], v186 offset:56320
	s_add_u32 s98, s54, 0xfffc0080
	s_addc_u32 s99, s55, -1
	global_load_lds_dwordx4 v0, s[98:99]
	s_mov_b32 m0, s63
	s_nop 0
	global_load_lds_dwordx4 v2, s[98:99]
	s_barrier
	s_waitcnt lgkmcnt(0)
	s_setprio 1
	s_waitcnt lgkmcnt(0)
	v_mfma_f32_16x16x32_bf16 v[60:63], v[124:127], v[140:143], v[60:63]
	v_mfma_f32_16x16x32_bf16 v[56:59], v[132:135], v[140:143], v[56:59]
	v_mfma_f32_16x16x32_bf16 v[44:47], v[124:127], v[152:155], v[44:47]
	v_mfma_f32_16x16x32_bf16 v[40:43], v[132:135], v[152:155], v[40:43]
	v_mfma_f32_16x16x32_bf16 v[28:31], v[124:127], v[188:191], v[28:31]
	v_mfma_f32_16x16x32_bf16 v[24:27], v[132:135], v[188:191], v[24:27]
	v_mfma_f32_16x16x32_bf16 v[12:15], v[124:127], v[222:225], v[12:15]
	v_mfma_f32_16x16x32_bf16 v[8:11], v[132:135], v[222:225], v[8:11]
	v_mfma_f32_16x16x32_bf16 v[60:63], v[128:131], v[148:151], v[60:63]
	v_mfma_f32_16x16x32_bf16 v[56:59], v[136:139], v[148:151], v[56:59]
	v_mfma_f32_16x16x32_bf16 v[44:47], v[128:131], v[156:159], v[44:47]
	v_mfma_f32_16x16x32_bf16 v[40:43], v[136:139], v[156:159], v[40:43]
	v_mfma_f32_16x16x32_bf16 v[28:31], v[128:131], v[192:195], v[28:31]
	v_mfma_f32_16x16x32_bf16 v[24:27], v[136:139], v[192:195], v[24:27]
	v_mfma_f32_16x16x32_bf16 v[12:15], v[128:131], v[226:229], v[12:15]
	v_mfma_f32_16x16x32_bf16 v[8:11], v[136:139], v[226:229], v[8:11]
	s_setprio 0
	s_barrier
	s_add_u32 s52, s52, 0x40080
	s_addc_u32 s53, s53, 0
	s_add_i32 s12, s26, s57
	s_add_i32 m0, s57, 0x1c000
	s_nop 0
	global_load_lds_dwordx4 v0, s[52:53]
	s_add_i32 m0, s57, 0x1e000
	s_nop 0
	global_load_lds_dwordx4 v2, s[52:53]
	s_waitcnt vmcnt(6)
	s_barrier
	s_setprio 1
	v_mfma_f32_16x16x32_bf16 v[68:71], v[230:233], v[140:143], v[68:71]
	v_mfma_f32_16x16x32_bf16 v[64:67], v[238:241], v[140:143], v[64:67]
	v_mfma_f32_16x16x32_bf16 v[52:55], v[230:233], v[152:155], v[52:55]
	v_mfma_f32_16x16x32_bf16 v[48:51], v[238:241], v[152:155], v[48:51]
	v_mfma_f32_16x16x32_bf16 v[36:39], v[230:233], v[188:191], v[36:39]
	v_mfma_f32_16x16x32_bf16 v[32:35], v[238:241], v[188:191], v[32:35]
	v_mfma_f32_16x16x32_bf16 v[20:23], v[230:233], v[222:225], v[20:23]
	v_mfma_f32_16x16x32_bf16 v[16:19], v[238:241], v[222:225], v[16:19]
	v_mfma_f32_16x16x32_bf16 v[68:71], v[234:237], v[148:151], v[68:71]
	v_mfma_f32_16x16x32_bf16 v[64:67], v[242:245], v[148:151], v[64:67]
	v_mfma_f32_16x16x32_bf16 v[52:55], v[234:237], v[156:159], v[52:55]
	v_mfma_f32_16x16x32_bf16 v[48:51], v[242:245], v[156:159], v[48:51]
	v_mfma_f32_16x16x32_bf16 v[36:39], v[234:237], v[192:195], v[36:39]
	v_mfma_f32_16x16x32_bf16 v[32:35], v[242:245], v[192:195], v[32:35]
	v_mfma_f32_16x16x32_bf16 v[20:23], v[234:237], v[226:229], v[20:23]
	v_mfma_f32_16x16x32_bf16 v[16:19], v[242:245], v[226:229], v[16:19]
	s_setprio 0
	s_add_i32 s73, s73, 2
	s_add_u32 s71, s71, 0x100
	s_addc_u32 s72, s72, 0
	s_add_u32 s50, s50, 0x100
	s_addc_u32 s51, s51, 0
	s_cmp_gt_u32 s73, 13
	s_cbranch_scc1 .LrotX_78
	s_cmp_lg_u32 s73, 12
	s_cselect_b64 s[52:53], -1, 0
	s_add_u32 s12, s50, 0xfffc0080
	s_addc_u32 s26, s51, -1
	s_and_b64 s[52:53], s[52:53], exec
	s_cselect_b32 s55, s26, s43
	s_cselect_b32 s54, s12, s42
	s_cselect_b32 s53, s72, s15
	s_cselect_b32 s52, s71, s69
.LrotX_78:
	s_cmp_gt_u32 s73, 13
	s_barrier
	s_cbranch_scc1 .LBB0_82
	s_cmp_lg_u32 s73, 12
	s_cbranch_scc1 .LmainW_78

; #define G_STAGE(bufoff, gbase) do { _Pragma("unroll") for (int _i = 0; _i < 2; ++_i) \
;         __builtin_amdgcn_global_load_lds((const unsigned*)((const char*)(gbase) + voff[_i]), (LAS unsigned*)(lds + (bufoff) + ldsw + _i * 8192), 16, 0, 0); } while (0)
; #define G_LDA(dst, b, h) do { _Pragma("unroll") for (int m = 0; m < 4; ++m) _Pragma("unroll") for (int k = 0; k < 2; ++k) dst[m][k] = *(const LAS bf16x8*)(lds + G_SA(b, h) + aoff + m * 2048 + k * 1024); } while (0)
; #define G_LDB(dst, b, h) do { _Pragma("unroll") for (int n = 0; n < 2; ++n) _Pragma("unroll") for (int k = 0; k < 2; ++k) dst[n][k] = *(const LAS bf16x8*)(lds + G_SB(b, h) + boff + n * 2048 + k * 1024); } while (0)
; #define G_MMA(ai, bj, At, Bt) do { __builtin_amdgcn_s_setprio(1); _Pragma("unroll") for (int m = 0; m < 4; ++m) _Pragma("unroll") for (int n = 0; n < 2; ++n) _Pragma("unroll") for (int k = 0; k < 2; ++k) \
;         acc[ai][bj][m][n] = MFMA16(Bt[n][k], At[m][k], acc[ai][bj][m][n]); __builtin_amdgcn_s_setprio(0); } while (0)
; #define G_WAIT_V(n) asm volatile("s_waitcnt vmcnt(" #n ")" ::: "memory")
; #define G_WAIT_L(n) asm volatile("s_waitcnt lgkmcnt(" #n ")" ::: "memory")
; #define G_BAR __builtin_amdgcn_s_barrier()
; #define G_SCHED __builtin_amdgcn_sched_barrier(0)
; template <class Epi>
; __device__ __forceinline__ void gemm_phase(LAS unsigned char* lds, const bf16_t* Ag, const bf16_t* Btg, const int K, const int nM, const int nN, const Epi& E) {
;     ...
;             G_LDB(B0, 0, 0); G_SCHED; G_LDA(At, 0, 0); G_STAGE(G_SA(1, 1), a1 + hstep);
;             G_WAIT_L(8); G_BAR; G_WAIT_L(0); G_MMA(0, 0, At, B0); G_BAR; G_SCHED;
;             G_LDB(B1, 0, 1); G_STAGE(G_SB(0, 0), b2);
;             G_BAR; G_WAIT_L(0); G_MMA(0, 1, At, B1); G_BAR;
;             G_LDA(At, 0, 1); G_STAGE(G_SA(0, 0), a2);
;             G_BAR; G_WAIT_L(0); G_MMA(1, 0, At, B0); G_BAR; G_SCHED;
;             G_STAGE(G_SB(0, 1), b2 + hstep);
;             G_WAIT_V(6); G_BAR; G_MMA(1, 1, At, B1); G_BAR;
.LmainW_153:
	ds_read_b128 v[144:147], v217
	ds_read_b128 v[148:151], v217 offset:1024
	ds_read_b128 v[152:155], v217 offset:2048
	ds_read_b128 v[156:159], v217 offset:3072
	s_add_i32 m0, s72, 0xc000
	ds_read_b128 v[160:163], v230
	ds_read_b128 v[164:167], v230 offset:1024
	ds_read_b128 v[168:171], v230 offset:2048
	ds_read_b128 v[172:175], v230 offset:3072
	ds_read_b128 v[180:183], v230 offset:4096
	ds_read_b128 v[184:187], v230 offset:5120
	ds_read_b128 v[188:191], v230 offset:6144
	global_load_lds_dwordx4 v138, s[64:65]
	s_add_i32 m0, s72, 0xe000
	ds_read_b128 v[192:195], v230 offset:7168
	global_load_lds_dwordx4 v136, s[64:65]
	s_waitcnt lgkmcnt(8)
	s_barrier
	s_waitcnt lgkmcnt(0)
	s_setprio 1
	s_waitcnt lgkmcnt(0)
	v_mfma_f32_16x16x32_bf16 v[132:135], v[144:147], v[160:163], v[132:135]
	v_mfma_f32_16x16x32_bf16 v[128:131], v[152:155], v[160:163], v[128:131]
	v_mfma_f32_16x16x32_bf16 v[116:119], v[144:147], v[168:171], v[116:119]
	v_mfma_f32_16x16x32_bf16 v[112:115], v[152:155], v[168:171], v[112:115]
	v_mfma_f32_16x16x32_bf16 v[100:103], v[144:147], v[180:183], v[100:103]
	v_mfma_f32_16x16x32_bf16 v[96:99], v[152:155], v[180:183], v[96:99]
	v_mfma_f32_16x16x32_bf16 v[84:87], v[144:147], v[188:191], v[84:87]
	v_mfma_f32_16x16x32_bf16 v[80:83], v[152:155], v[188:191], v[80:83]
	v_mfma_f32_16x16x32_bf16 v[132:135], v[148:151], v[164:167], v[132:135]
	v_mfma_f32_16x16x32_bf16 v[128:131], v[156:159], v[164:167], v[128:131]
	v_mfma_f32_16x16x32_bf16 v[116:119], v[148:151], v[172:175], v[116:119]
	v_mfma_f32_16x16x32_bf16 v[112:115], v[156:159], v[172:175], v[112:115]
	v_mfma_f32_16x16x32_bf16 v[100:103], v[148:151], v[184:187], v[100:103]
	v_mfma_f32_16x16x32_bf16 v[96:99], v[156:159], v[184:187], v[96:99]
	v_mfma_f32_16x16x32_bf16 v[84:87], v[148:151], v[192:195], v[84:87]
	v_mfma_f32_16x16x32_bf16 v[80:83], v[156:159], v[192:195], v[80:83]
	s_setprio 0
	s_barrier
	s_add_i32 m0, s21, 0x10000
	ds_read_b128 v[232:235], v217 offset:16384
	ds_read_b128 v[236:239], v217 offset:17408
	ds_read_b128 v[240:243], v217 offset:18432
	global_load_lds_dwordx4 v0, s[68:69]
	s_add_i32 m0, s21, 0x12000
	ds_read_b128 v[244:247], v217 offset:19456
	global_load_lds_dwordx4 v2, s[68:69]
	s_barrier
	s_waitcnt lgkmcnt(0)
	s_setprio 1
	s_waitcnt lgkmcnt(0)
	v_mfma_f32_16x16x32_bf16 v[124:127], v[232:235], v[160:163], v[124:127]
	v_mfma_f32_16x16x32_bf16 v[120:123], v[240:243], v[160:163], v[120:123]
	v_mfma_f32_16x16x32_bf16 v[108:111], v[232:235], v[168:171], v[108:111]
	v_mfma_f32_16x16x32_bf16 v[104:107], v[240:243], v[168:171], v[104:107]
	v_mfma_f32_16x16x32_bf16 v[92:95], v[232:235], v[180:183], v[92:95]
	v_mfma_f32_16x16x32_bf16 v[88:91], v[240:243], v[180:183], v[88:91]
	v_mfma_f32_16x16x32_bf16 v[76:79], v[232:235], v[188:191], v[76:79]
	v_mfma_f32_16x16x32_bf16 v[72:75], v[240:243], v[188:191], v[72:75]
	v_mfma_f32_16x16x32_bf16 v[124:127], v[236:239], v[164:167], v[124:127]
	v_mfma_f32_16x16x32_bf16 v[120:123], v[244:247], v[164:167], v[120:123]
	v_mfma_f32_16x16x32_bf16 v[108:111], v[236:239], v[172:175], v[108:111]
	v_mfma_f32_16x16x32_bf16 v[104:107], v[244:247], v[172:175], v[104:107]
	v_mfma_f32_16x16x32_bf16 v[92:95], v[236:239], v[184:187], v[92:95]
	v_mfma_f32_16x16x32_bf16 v[88:91], v[244:247], v[184:187], v[88:91]
	v_mfma_f32_16x16x32_bf16 v[76:79], v[236:239], v[192:195], v[76:79]
	v_mfma_f32_16x16x32_bf16 v[72:75], v[244:247], v[192:195], v[72:75]
	s_setprio 0
	s_mov_b32 m0, s72
	s_barrier
	ds_read_b128 v[160:163], v230 offset:16384
	ds_read_b128 v[164:167], v230 offset:17408
	ds_read_b128 v[168:171], v230 offset:18432
	ds_read_b128 v[172:175], v230 offset:19456
	ds_read_b128 v[180:183], v230 offset:20480
	ds_read_b128 v[184:187], v230 offset:21504
	ds_read_b128 v[188:191], v230 offset:22528
	global_load_lds_dwordx4 v0, s[70:71]
	s_mov_b32 m0, s73
	ds_read_b128 v[192:195], v230 offset:23552
	global_load_lds_dwordx4 v2, s[70:71]
	s_barrier
	s_waitcnt lgkmcnt(0)
	s_setprio 1
	s_waitcnt lgkmcnt(0)
	v_mfma_f32_16x16x32_bf16 v[68:71], v[144:147], v[160:163], v[68:71]
	v_mfma_f32_16x16x32_bf16 v[64:67], v[152:155], v[160:163], v[64:67]
	v_mfma_f32_16x16x32_bf16 v[52:55], v[144:147], v[168:171], v[52:55]
	v_mfma_f32_16x16x32_bf16 v[48:51], v[152:155], v[168:171], v[48:51]
	v_mfma_f32_16x16x32_bf16 v[36:39], v[144:147], v[180:183], v[36:39]
	v_mfma_f32_16x16x32_bf16 v[32:35], v[152:155], v[180:183], v[32:35]
	v_mfma_f32_16x16x32_bf16 v[20:23], v[144:147], v[188:191], v[20:23]
	v_mfma_f32_16x16x32_bf16 v[16:19], v[152:155], v[188:191], v[16:19]
	v_mfma_f32_16x16x32_bf16 v[68:71], v[148:151], v[164:167], v[68:71]
	v_mfma_f32_16x16x32_bf16 v[64:67], v[156:159], v[164:167], v[64:67]
	v_mfma_f32_16x16x32_bf16 v[52:55], v[148:151], v[172:175], v[52:55]
	v_mfma_f32_16x16x32_bf16 v[48:51], v[156:159], v[172:175], v[48:51]
	v_mfma_f32_16x16x32_bf16 v[36:39], v[148:151], v[184:187], v[36:39]
	v_mfma_f32_16x16x32_bf16 v[32:35], v[156:159], v[184:187], v[32:35]
	v_mfma_f32_16x16x32_bf16 v[20:23], v[148:151], v[192:195], v[20:23]
	v_mfma_f32_16x16x32_bf16 v[16:19], v[156:159], v[192:195], v[16:19]
	s_setprio 0
	s_barrier
	s_add_u32 s64, s68, 0x40000
	s_addc_u32 s65, s69, 0
	s_add_i32 m0, s21, 0x14000
	s_nop 0
	global_load_lds_dwordx4 v0, s[64:65]
	s_add_i32 m0, s21, 0x16000
	s_nop 0
	global_load_lds_dwordx4 v2, s[64:65]
	s_waitcnt vmcnt(6)
	s_barrier
; #define G_STAGE(bufoff, gbase) do { _Pragma("unroll") for (int _i = 0; _i < 2; ++_i) \
;         __builtin_amdgcn_global_load_lds((const unsigned*)((const char*)(gbase) + voff[_i]), (LAS unsigned*)(lds + (bufoff) + ldsw + _i * 8192), 16, 0, 0); } while (0)
; #define G_LDA(dst, b, h) do { _Pragma("unroll") for (int m = 0; m < 4; ++m) _Pragma("unroll") for (int k = 0; k < 2; ++k) dst[m][k] = *(const LAS bf16x8*)(lds + G_SA(b, h) + aoff + m * 2048 + k * 1024); } while (0)
; #define G_LDB(dst, b, h) do { _Pragma("unroll") for (int n = 0; n < 2; ++n) _Pragma("unroll") for (int k = 0; k < 2; ++k) dst[n][k] = *(const LAS bf16x8*)(lds + G_SB(b, h) + boff + n * 2048 + k * 1024); } while (0)
; #define G_MMA(ai, bj, At, Bt) do { __builtin_amdgcn_s_setprio(1); _Pragma("unroll") for (int m = 0; m < 4; ++m) _Pragma("unroll") for (int n = 0; n < 2; ++n) _Pragma("unroll") for (int k = 0; k < 2; ++k) \
;         acc[ai][bj][m][n] = MFMA16(Bt[n][k], At[m][k], acc[ai][bj][m][n]); __builtin_amdgcn_s_setprio(0); } while (0)
; #define G_WAIT_V(n) asm volatile("s_waitcnt vmcnt(" #n ")" ::: "memory")
; #define G_WAIT_L(n) asm volatile("s_waitcnt lgkmcnt(" #n ")" ::: "memory")
; #define G_BAR __builtin_amdgcn_s_barrier()
; #define G_SCHED __builtin_amdgcn_sched_barrier(0)
; template <class Epi>
; __device__ __forceinline__ void gemm_phase(LAS unsigned char* lds, const bf16_t* Ag, const bf16_t* Btg, const int K, const int nM, const int nN, const Epi& E) {
;     ...
;             G_WAIT_V(6); G_BAR; G_MMA(1, 1, At, B1); G_BAR;
;             G_LDB(B0, 1, 0); G_SCHED; G_LDA(At, 1, 0); G_STAGE(G_SA(0, 1), a2 + hstep);
;             G_WAIT_L(8); G_BAR; G_WAIT_L(0); G_MMA(0, 0, At, B0); G_BAR; G_SCHED;
;             G_LDB(B1, 1, 1); G_STAGE(G_SB(1, 0), b3);
;             G_BAR; G_WAIT_L(0); G_MMA(0, 1, At, B1); G_BAR;
;             G_LDA(At, 1, 1); G_STAGE(G_SA(1, 0), a3);
;             G_BAR; G_WAIT_L(0); G_MMA(1, 0, At, B0); G_BAR; G_SCHED;
	s_setprio 1
	v_mfma_f32_16x16x32_bf16 v[60:63], v[232:235], v[160:163], v[60:63]
	v_mfma_f32_16x16x32_bf16 v[56:59], v[240:243], v[160:163], v[56:59]
	v_mfma_f32_16x16x32_bf16 v[44:47], v[232:235], v[168:171], v[44:47]
	v_mfma_f32_16x16x32_bf16 v[40:43], v[240:243], v[168:171], v[40:43]
	v_mfma_f32_16x16x32_bf16 v[28:31], v[232:235], v[180:183], v[28:31]
	v_mfma_f32_16x16x32_bf16 v[24:27], v[240:243], v[180:183], v[24:27]
	v_mfma_f32_16x16x32_bf16 v[12:15], v[232:235], v[188:191], v[12:15]
	v_mfma_f32_16x16x32_bf16 v[8:11], v[240:243], v[188:191], v[8:11]
	v_mfma_f32_16x16x32_bf16 v[60:63], v[236:239], v[164:167], v[60:63]
	v_mfma_f32_16x16x32_bf16 v[56:59], v[244:247], v[164:167], v[56:59]
	v_mfma_f32_16x16x32_bf16 v[44:47], v[236:239], v[172:175], v[44:47]
	v_mfma_f32_16x16x32_bf16 v[40:43], v[244:247], v[172:175], v[40:43]
	v_mfma_f32_16x16x32_bf16 v[28:31], v[236:239], v[184:187], v[28:31]
	v_mfma_f32_16x16x32_bf16 v[24:27], v[244:247], v[184:187], v[24:27]
	v_mfma_f32_16x16x32_bf16 v[12:15], v[236:239], v[192:195], v[12:15]
	v_mfma_f32_16x16x32_bf16 v[8:11], v[244:247], v[192:195], v[8:11]
	s_setprio 0
	s_barrier
	ds_read_b128 v[144:147], v217 offset:32768
	ds_read_b128 v[148:151], v217 offset:33792
	ds_read_b128 v[152:155], v217 offset:34816
	ds_read_b128 v[156:159], v217 offset:35840
	s_add_u32 s64, s70, 0x40000
	s_addc_u32 s65, s71, 0
	s_mov_b32 m0, s74
	ds_read_b128 v[160:163], v230 offset:32768
	ds_read_b128 v[164:167], v230 offset:33792
	ds_read_b128 v[168:171], v230 offset:34816
	ds_read_b128 v[172:175], v230 offset:35840
	ds_read_b128 v[180:183], v230 offset:36864
	ds_read_b128 v[184:187], v230 offset:37888
	ds_read_b128 v[188:191], v230 offset:38912
	global_load_lds_dwordx4 v0, s[64:65]
	s_mov_b32 m0, s75
	ds_read_b128 v[192:195], v230 offset:39936
	global_load_lds_dwordx4 v2, s[64:65]
	s_waitcnt lgkmcnt(8)
	s_barrier
	s_waitcnt lgkmcnt(0)
	s_setprio 1
	s_waitcnt lgkmcnt(0)
	v_mfma_f32_16x16x32_bf16 v[132:135], v[144:147], v[160:163], v[132:135]
	v_mfma_f32_16x16x32_bf16 v[128:131], v[152:155], v[160:163], v[128:131]
	v_mfma_f32_16x16x32_bf16 v[116:119], v[144:147], v[168:171], v[116:119]
	v_mfma_f32_16x16x32_bf16 v[112:115], v[152:155], v[168:171], v[112:115]
	v_mfma_f32_16x16x32_bf16 v[100:103], v[144:147], v[180:183], v[100:103]
	v_mfma_f32_16x16x32_bf16 v[96:99], v[152:155], v[180:183], v[96:99]
	v_mfma_f32_16x16x32_bf16 v[84:87], v[144:147], v[188:191], v[84:87]
	v_mfma_f32_16x16x32_bf16 v[80:83], v[152:155], v[188:191], v[80:83]
	v_mfma_f32_16x16x32_bf16 v[132:135], v[148:151], v[164:167], v[132:135]
	v_mfma_f32_16x16x32_bf16 v[128:131], v[156:159], v[164:167], v[128:131]
	v_mfma_f32_16x16x32_bf16 v[116:119], v[148:151], v[172:175], v[116:119]
	v_mfma_f32_16x16x32_bf16 v[112:115], v[156:159], v[172:175], v[112:115]
	v_mfma_f32_16x16x32_bf16 v[100:103], v[148:151], v[184:187], v[100:103]
	v_mfma_f32_16x16x32_bf16 v[96:99], v[156:159], v[184:187], v[96:99]
	v_mfma_f32_16x16x32_bf16 v[84:87], v[148:151], v[192:195], v[84:87]
	v_mfma_f32_16x16x32_bf16 v[80:83], v[156:159], v[192:195], v[80:83]
	s_setprio 0
	s_barrier
	s_add_i32 s26, 0, 0x1c000
	s_add_i32 m0, s21, 0x18000
	ds_read_b128 v[232:235], v217 offset:49152
	ds_read_b128 v[236:239], v217 offset:50176
	ds_read_b128 v[240:243], v217 offset:51200
	ds_read_b128 v[244:247], v217 offset:52224
	s_add_u32 s98, s68, 0x80
	s_addc_u32 s99, s69, 0
	global_load_lds_dwordx4 v0, s[98:99]
	s_add_i32 m0, s21, 0x1a000
	s_nop 0
	global_load_lds_dwordx4 v2, s[98:99]
	s_barrier
	s_waitcnt lgkmcnt(0)
	s_setprio 1
	s_waitcnt lgkmcnt(0)
	v_mfma_f32_16x16x32_bf16 v[124:127], v[232:235], v[160:163], v[124:127]
	v_mfma_f32_16x16x32_bf16 v[120:123], v[240:243], v[160:163], v[120:123]
	v_mfma_f32_16x16x32_bf16 v[108:111], v[232:235], v[168:171], v[108:111]
	v_mfma_f32_16x16x32_bf16 v[104:107], v[240:243], v[168:171], v[104:107]
	v_mfma_f32_16x16x32_bf16 v[92:95], v[232:235], v[180:183], v[92:95]
	v_mfma_f32_16x16x32_bf16 v[88:91], v[240:243], v[180:183], v[88:91]
	v_mfma_f32_16x16x32_bf16 v[76:79], v[232:235], v[188:191], v[76:79]
	v_mfma_f32_16x16x32_bf16 v[72:75], v[240:243], v[188:191], v[72:75]
	v_mfma_f32_16x16x32_bf16 v[124:127], v[236:239], v[164:167], v[124:127]
	v_mfma_f32_16x16x32_bf16 v[120:123], v[244:247], v[164:167], v[120:123]
	v_mfma_f32_16x16x32_bf16 v[108:111], v[236:239], v[172:175], v[108:111]
	v_mfma_f32_16x16x32_bf16 v[104:107], v[244:247], v[172:175], v[104:107]
	v_mfma_f32_16x16x32_bf16 v[92:95], v[236:239], v[184:187], v[92:95]
	v_mfma_f32_16x16x32_bf16 v[88:91], v[244:247], v[184:187], v[88:91]
	v_mfma_f32_16x16x32_bf16 v[76:79], v[236:239], v[192:195], v[76:79]
	v_mfma_f32_16x16x32_bf16 v[72:75], v[244:247], v[192:195], v[72:75]
	s_setprio 0
	s_mov_b32 m0, s76
	s_barrier
; #define G_STAGE(bufoff, gbase) do { _Pragma("unroll") for (int _i = 0; _i < 2; ++_i) \
;         __builtin_amdgcn_global_load_lds((const unsigned*)((const char*)(gbase) + voff[_i]), (LAS unsigned*)(lds + (bufoff) + ldsw + _i * 8192), 16, 0, 0); } while (0)
; #define G_MMA(ai, bj, At, Bt) do { __builtin_amdgcn_s_setprio(1); _Pragma("unroll") for (int m = 0; m < 4; ++m) _Pragma("unroll") for (int n = 0; n < 2; ++n) _Pragma("unroll") for (int k = 0; k < 2; ++k) \
;         acc[ai][bj][m][n] = MFMA16(Bt[n][k], At[m][k], acc[ai][bj][m][n]); __builtin_amdgcn_s_setprio(0); } while (0)
; #define G_WAIT_V(n) asm volatile("s_waitcnt vmcnt(" #n ")" ::: "memory")
; #define G_WAIT_L(n) asm volatile("s_waitcnt lgkmcnt(" #n ")" ::: "memory")
; #define G_BAR __builtin_amdgcn_s_barrier()
; #define G_SCHED __builtin_amdgcn_sched_barrier(0)
; template <class Epi>
; __device__ __forceinline__ void gemm_phase(LAS unsigned char* lds, const bf16_t* Ag, const bf16_t* Btg, const int K, const int nM, const int nN, const Epi& E) {
;     ...
;         for (int t = 0; t < nt; t += 2) {
;             const bool last = (t == nt - 2);
;             const char* a1 = cA + (size_t)(t + 1) * kstep;
;             const char* a2 = last ? nA : cA + (size_t)(t + 2) * kstep; const char* b2 = last ? nB : cB + (size_t)(t + 2) * kstep;
;             const char* a3 = a2 + kstep; const char* b3 = b2 + kstep;
;     ...
;             G_BAR; G_WAIT_L(0); G_MMA(1, 0, At, B0); G_BAR; G_SCHED;
;             G_STAGE(G_SB(1, 1), b3 + hstep);
;             G_WAIT_V(6); G_BAR; G_MMA(1, 1, At, B1); G_BAR;
	ds_read_b128 v[160:163], v230 offset:49152
	ds_read_b128 v[164:167], v230 offset:50176
	ds_read_b128 v[168:171], v230 offset:51200
	ds_read_b128 v[172:175], v230 offset:52224
	ds_read_b128 v[180:183], v230 offset:53248
	ds_read_b128 v[184:187], v230 offset:54272
	ds_read_b128 v[188:191], v230 offset:55296
	ds_read_b128 v[192:195], v230 offset:56320
	s_add_u32 s98, s70, 0x80
	s_addc_u32 s99, s71, 0
	global_load_lds_dwordx4 v0, s[98:99]
	s_mov_b32 m0, s77
	s_nop 0
	global_load_lds_dwordx4 v2, s[98:99]
	s_barrier
	s_waitcnt lgkmcnt(0)
	s_setprio 1
	s_waitcnt lgkmcnt(0)
	v_mfma_f32_16x16x32_bf16 v[68:71], v[144:147], v[160:163], v[68:71]
	v_mfma_f32_16x16x32_bf16 v[64:67], v[152:155], v[160:163], v[64:67]
	v_mfma_f32_16x16x32_bf16 v[52:55], v[144:147], v[168:171], v[52:55]
	v_mfma_f32_16x16x32_bf16 v[48:51], v[152:155], v[168:171], v[48:51]
	v_mfma_f32_16x16x32_bf16 v[36:39], v[144:147], v[180:183], v[36:39]
	v_mfma_f32_16x16x32_bf16 v[32:35], v[152:155], v[180:183], v[32:35]
	v_mfma_f32_16x16x32_bf16 v[20:23], v[144:147], v[188:191], v[20:23]
	v_mfma_f32_16x16x32_bf16 v[16:19], v[152:155], v[188:191], v[16:19]
	v_mfma_f32_16x16x32_bf16 v[68:71], v[148:151], v[164:167], v[68:71]
	v_mfma_f32_16x16x32_bf16 v[64:67], v[156:159], v[164:167], v[64:67]
	v_mfma_f32_16x16x32_bf16 v[52:55], v[148:151], v[172:175], v[52:55]
	v_mfma_f32_16x16x32_bf16 v[48:51], v[156:159], v[172:175], v[48:51]
	v_mfma_f32_16x16x32_bf16 v[36:39], v[148:151], v[184:187], v[36:39]
	v_mfma_f32_16x16x32_bf16 v[32:35], v[156:159], v[184:187], v[32:35]
	v_mfma_f32_16x16x32_bf16 v[20:23], v[148:151], v[192:195], v[20:23]
	v_mfma_f32_16x16x32_bf16 v[16:19], v[156:159], v[192:195], v[16:19]
	s_setprio 0
	s_barrier
	s_add_u32 s64, s68, 0x40080
	s_addc_u32 s65, s69, 0
	s_add_i32 s12, s26, s21
	s_add_i32 m0, s21, 0x1c000
	s_nop 0
	global_load_lds_dwordx4 v0, s[64:65]
	s_add_i32 m0, s21, 0x1e000
	s_nop 0
	global_load_lds_dwordx4 v2, s[64:65]
	s_waitcnt vmcnt(6)
	s_barrier
	s_setprio 1
	v_mfma_f32_16x16x32_bf16 v[60:63], v[232:235], v[160:163], v[60:63]
	v_mfma_f32_16x16x32_bf16 v[56:59], v[240:243], v[160:163], v[56:59]
	v_mfma_f32_16x16x32_bf16 v[44:47], v[232:235], v[168:171], v[44:47]
	v_mfma_f32_16x16x32_bf16 v[40:43], v[240:243], v[168:171], v[40:43]
	v_mfma_f32_16x16x32_bf16 v[28:31], v[232:235], v[180:183], v[28:31]
	v_mfma_f32_16x16x32_bf16 v[24:27], v[240:243], v[180:183], v[24:27]
	v_mfma_f32_16x16x32_bf16 v[12:15], v[232:235], v[188:191], v[12:15]
	v_mfma_f32_16x16x32_bf16 v[8:11], v[240:243], v[188:191], v[8:11]
	v_mfma_f32_16x16x32_bf16 v[60:63], v[236:239], v[164:167], v[60:63]
	v_mfma_f32_16x16x32_bf16 v[56:59], v[244:247], v[164:167], v[56:59]
	v_mfma_f32_16x16x32_bf16 v[44:47], v[236:239], v[172:175], v[44:47]
	v_mfma_f32_16x16x32_bf16 v[40:43], v[244:247], v[172:175], v[40:43]
	v_mfma_f32_16x16x32_bf16 v[28:31], v[236:239], v[184:187], v[28:31]
	v_mfma_f32_16x16x32_bf16 v[24:27], v[244:247], v[184:187], v[24:27]
	v_mfma_f32_16x16x32_bf16 v[12:15], v[236:239], v[192:195], v[12:15]
	v_mfma_f32_16x16x32_bf16 v[8:11], v[244:247], v[192:195], v[8:11]
	s_setprio 0
	s_add_i32 s42, s42, 2
	s_add_u32 s57, s57, 0x100
	s_addc_u32 s61, s61, 0
	s_mov_b64 s[64:65], s[66:67]
	s_cmp_gt_u32 s42, 13
	s_cbranch_scc1 .LrotX_153
	s_cmp_lg_u32 s42, 12
	s_cselect_b64 s[68:69], -1, 0
	s_add_u32 s66, s64, 0x100
	s_addc_u32 s67, s65, 0
	s_and_b64 s[68:69], s[68:69], exec
	s_cselect_b32 s71, s67, s55
	s_cselect_b32 s70, s66, s54
	s_cselect_b32 s69, s61, s14
	s_cselect_b32 s68, s57, s15
.LrotX_153:
	s_cmp_gt_u32 s42, 13
	s_barrier
	s_cbranch_scc1 .LBB0_157
	s_cmp_lg_u32 s42, 12
	s_cbranch_scc1 .LmainW_153

; #define G_STAGE(bufoff, gbase) do { _Pragma("unroll") for (int _i = 0; _i < 2; ++_i) \
;         __builtin_amdgcn_global_load_lds((const unsigned*)((const char*)(gbase) + voff[_i]), (LAS unsigned*)(lds + (bufoff) + ldsw + _i * 8192), 16, 0, 0); } while (0)
; #define G_LDA(dst, b, h) do { _Pragma("unroll") for (int m = 0; m < 4; ++m) _Pragma("unroll") for (int k = 0; k < 2; ++k) dst[m][k] = *(const LAS bf16x8*)(lds + G_SA(b, h) + aoff + m * 2048 + k * 1024); } while (0)
; #define G_LDB(dst, b, h) do { _Pragma("unroll") for (int n = 0; n < 2; ++n) _Pragma("unroll") for (int k = 0; k < 2; ++k) dst[n][k] = *(const LAS bf16x8*)(lds + G_SB(b, h) + boff + n * 2048 + k * 1024); } while (0)
; #define G_MMA(ai, bj, At, Bt) do { __builtin_amdgcn_s_setprio(1); _Pragma("unroll") for (int m = 0; m < 4; ++m) _Pragma("unroll") for (int n = 0; n < 2; ++n) _Pragma("unroll") for (int k = 0; k < 2; ++k) \
;         acc[ai][bj][m][n] = MFMA16(Bt[n][k], At[m][k], acc[ai][bj][m][n]); __builtin_amdgcn_s_setprio(0); } while (0)
; #define G_WAIT_V(n) asm volatile("s_waitcnt vmcnt(" #n ")" ::: "memory")
; #define G_WAIT_L(n) asm volatile("s_waitcnt lgkmcnt(" #n ")" ::: "memory")
; #define G_BAR __builtin_amdgcn_s_barrier()
; #define G_SCHED __builtin_amdgcn_sched_barrier(0)
; template <class Epi>
; __device__ __forceinline__ void gemm_phase(LAS unsigned char* lds, const bf16_t* Ag, const bf16_t* Btg, const int K, const int nM, const int nN, const Epi& E) {
;     ...
;             G_LDB(B0, 0, 0); G_SCHED; G_LDA(At, 0, 0); G_STAGE(G_SA(1, 1), a1 + hstep);
;             G_WAIT_L(8); G_BAR; G_WAIT_L(0); G_MMA(0, 0, At, B0); G_BAR; G_SCHED;
;             G_LDB(B1, 0, 1); G_STAGE(G_SB(0, 0), b2);
;             G_BAR; G_WAIT_L(0); G_MMA(0, 1, At, B1); G_BAR;
;             G_LDA(At, 0, 1); G_STAGE(G_SA(0, 0), a2);
;             G_BAR; G_WAIT_L(0); G_MMA(1, 0, At, B0); G_BAR; G_SCHED;
;             G_STAGE(G_SB(0, 1), b2 + hstep);
;             G_WAIT_V(6); G_BAR; G_MMA(1, 1, At, B1); G_BAR;
.LmainW_744:
	ds_read_b128 v[140:143], v217
	ds_read_b128 v[144:147], v217 offset:1024
	ds_read_b128 v[148:151], v217 offset:2048
	ds_read_b128 v[152:155], v217 offset:3072
	s_add_i32 m0, s66, 0xc000
	ds_read_b128 v[156:159], v174
	ds_read_b128 v[160:163], v174 offset:1024
	ds_read_b128 v[180:183], v174 offset:2048
	ds_read_b128 v[184:187], v174 offset:3072
	ds_read_b128 v[188:191], v174 offset:4096
	ds_read_b128 v[192:195], v174 offset:5120
	ds_read_b128 v[222:225], v174 offset:6144
	global_load_lds_dwordx4 v138, s[56:57]
	s_add_i32 m0, s66, 0xe000
	ds_read_b128 v[226:229], v174 offset:7168
	global_load_lds_dwordx4 v136, s[56:57]
	s_waitcnt lgkmcnt(8)
	s_barrier
	s_waitcnt lgkmcnt(0)
	s_setprio 1
	s_waitcnt lgkmcnt(0)
	v_mfma_f32_16x16x32_bf16 v[132:135], v[140:143], v[156:159], v[132:135]
	v_mfma_f32_16x16x32_bf16 v[128:131], v[148:151], v[156:159], v[128:131]
	v_mfma_f32_16x16x32_bf16 v[116:119], v[140:143], v[180:183], v[116:119]
	v_mfma_f32_16x16x32_bf16 v[112:115], v[148:151], v[180:183], v[112:115]
	v_mfma_f32_16x16x32_bf16 v[100:103], v[140:143], v[188:191], v[100:103]
	v_mfma_f32_16x16x32_bf16 v[96:99], v[148:151], v[188:191], v[96:99]
	v_mfma_f32_16x16x32_bf16 v[84:87], v[140:143], v[222:225], v[84:87]
	v_mfma_f32_16x16x32_bf16 v[80:83], v[148:151], v[222:225], v[80:83]
	v_mfma_f32_16x16x32_bf16 v[132:135], v[144:147], v[160:163], v[132:135]
	v_mfma_f32_16x16x32_bf16 v[128:131], v[152:155], v[160:163], v[128:131]
	v_mfma_f32_16x16x32_bf16 v[116:119], v[144:147], v[184:187], v[116:119]
	v_mfma_f32_16x16x32_bf16 v[112:115], v[152:155], v[184:187], v[112:115]
	v_mfma_f32_16x16x32_bf16 v[100:103], v[144:147], v[192:195], v[100:103]
	v_mfma_f32_16x16x32_bf16 v[96:99], v[152:155], v[192:195], v[96:99]
	v_mfma_f32_16x16x32_bf16 v[84:87], v[144:147], v[226:229], v[84:87]
	v_mfma_f32_16x16x32_bf16 v[80:83], v[152:155], v[226:229], v[80:83]
	s_setprio 0
	s_barrier
	s_add_i32 m0, s65, 0x10000
	ds_read_b128 v[230:233], v217 offset:16384
	ds_read_b128 v[234:237], v217 offset:17408
	ds_read_b128 v[238:241], v217 offset:18432
	global_load_lds_dwordx4 v0, s[60:61]
	s_add_i32 m0, s65, 0x12000
	ds_read_b128 v[242:245], v217 offset:19456
	global_load_lds_dwordx4 v2, s[60:61]
	s_barrier
	s_waitcnt lgkmcnt(0)
	s_setprio 1
	s_waitcnt lgkmcnt(0)
	v_mfma_f32_16x16x32_bf16 v[124:127], v[230:233], v[156:159], v[124:127]
	v_mfma_f32_16x16x32_bf16 v[120:123], v[238:241], v[156:159], v[120:123]
	v_mfma_f32_16x16x32_bf16 v[108:111], v[230:233], v[180:183], v[108:111]
	v_mfma_f32_16x16x32_bf16 v[104:107], v[238:241], v[180:183], v[104:107]
	v_mfma_f32_16x16x32_bf16 v[92:95], v[230:233], v[188:191], v[92:95]
	v_mfma_f32_16x16x32_bf16 v[88:91], v[238:241], v[188:191], v[88:91]
	v_mfma_f32_16x16x32_bf16 v[76:79], v[230:233], v[222:225], v[76:79]
	v_mfma_f32_16x16x32_bf16 v[72:75], v[238:241], v[222:225], v[72:75]
	v_mfma_f32_16x16x32_bf16 v[124:127], v[234:237], v[160:163], v[124:127]
	v_mfma_f32_16x16x32_bf16 v[120:123], v[242:245], v[160:163], v[120:123]
	v_mfma_f32_16x16x32_bf16 v[108:111], v[234:237], v[184:187], v[108:111]
	v_mfma_f32_16x16x32_bf16 v[104:107], v[242:245], v[184:187], v[104:107]
	v_mfma_f32_16x16x32_bf16 v[92:95], v[234:237], v[192:195], v[92:95]
	v_mfma_f32_16x16x32_bf16 v[88:91], v[242:245], v[192:195], v[88:91]
	v_mfma_f32_16x16x32_bf16 v[76:79], v[234:237], v[226:229], v[76:79]
	v_mfma_f32_16x16x32_bf16 v[72:75], v[242:245], v[226:229], v[72:75]
	s_setprio 0
	s_mov_b32 m0, s66
	s_barrier
	ds_read_b128 v[156:159], v174 offset:16384
	ds_read_b128 v[160:163], v174 offset:17408
	ds_read_b128 v[180:183], v174 offset:18432
	ds_read_b128 v[184:187], v174 offset:19456
	ds_read_b128 v[188:191], v174 offset:20480
	ds_read_b128 v[192:195], v174 offset:21504
	ds_read_b128 v[222:225], v174 offset:22528
	global_load_lds_dwordx4 v0, s[62:63]
	s_mov_b32 m0, s67
	ds_read_b128 v[226:229], v174 offset:23552
	global_load_lds_dwordx4 v2, s[62:63]
	s_barrier
	s_waitcnt lgkmcnt(0)
	s_setprio 1
	s_waitcnt lgkmcnt(0)
	v_mfma_f32_16x16x32_bf16 v[68:71], v[140:143], v[156:159], v[68:71]
	v_mfma_f32_16x16x32_bf16 v[64:67], v[148:151], v[156:159], v[64:67]
	v_mfma_f32_16x16x32_bf16 v[52:55], v[140:143], v[180:183], v[52:55]
	v_mfma_f32_16x16x32_bf16 v[48:51], v[148:151], v[180:183], v[48:51]
	v_mfma_f32_16x16x32_bf16 v[36:39], v[140:143], v[188:191], v[36:39]
	v_mfma_f32_16x16x32_bf16 v[32:35], v[148:151], v[188:191], v[32:35]
	v_mfma_f32_16x16x32_bf16 v[20:23], v[140:143], v[222:225], v[20:23]
	v_mfma_f32_16x16x32_bf16 v[16:19], v[148:151], v[222:225], v[16:19]
	v_mfma_f32_16x16x32_bf16 v[68:71], v[144:147], v[160:163], v[68:71]
	v_mfma_f32_16x16x32_bf16 v[64:67], v[152:155], v[160:163], v[64:67]
	v_mfma_f32_16x16x32_bf16 v[52:55], v[144:147], v[184:187], v[52:55]
	v_mfma_f32_16x16x32_bf16 v[48:51], v[152:155], v[184:187], v[48:51]
	v_mfma_f32_16x16x32_bf16 v[36:39], v[144:147], v[192:195], v[36:39]
	v_mfma_f32_16x16x32_bf16 v[32:35], v[152:155], v[192:195], v[32:35]
	v_mfma_f32_16x16x32_bf16 v[20:23], v[144:147], v[226:229], v[20:23]
	v_mfma_f32_16x16x32_bf16 v[16:19], v[152:155], v[226:229], v[16:19]
	s_setprio 0
	s_barrier
	s_add_u32 s56, s60, 0x100000
	s_addc_u32 s57, s61, 0
	s_add_i32 m0, s65, 0x14000
	s_nop 0
	global_load_lds_dwordx4 v0, s[56:57]
	s_add_i32 m0, s65, 0x16000
	s_nop 0
	global_load_lds_dwordx4 v2, s[56:57]
	s_waitcnt vmcnt(6)
	s_barrier
; #define G_STAGE(bufoff, gbase) do { _Pragma("unroll") for (int _i = 0; _i < 2; ++_i) \
;         __builtin_amdgcn_global_load_lds((const unsigned*)((const char*)(gbase) + voff[_i]), (LAS unsigned*)(lds + (bufoff) + ldsw + _i * 8192), 16, 0, 0); } while (0)
; #define G_LDA(dst, b, h) do { _Pragma("unroll") for (int m = 0; m < 4; ++m) _Pragma("unroll") for (int k = 0; k < 2; ++k) dst[m][k] = *(const LAS bf16x8*)(lds + G_SA(b, h) + aoff + m * 2048 + k * 1024); } while (0)
; #define G_LDB(dst, b, h) do { _Pragma("unroll") for (int n = 0; n < 2; ++n) _Pragma("unroll") for (int k = 0; k < 2; ++k) dst[n][k] = *(const LAS bf16x8*)(lds + G_SB(b, h) + boff + n * 2048 + k * 1024); } while (0)
; #define G_MMA(ai, bj, At, Bt) do { __builtin_amdgcn_s_setprio(1); _Pragma("unroll") for (int m = 0; m < 4; ++m) _Pragma("unroll") for (int n = 0; n < 2; ++n) _Pragma("unroll") for (int k = 0; k < 2; ++k) \
;         acc[ai][bj][m][n] = MFMA16(Bt[n][k], At[m][k], acc[ai][bj][m][n]); __builtin_amdgcn_s_setprio(0); } while (0)
; #define G_WAIT_V(n) asm volatile("s_waitcnt vmcnt(" #n ")" ::: "memory")
; #define G_WAIT_L(n) asm volatile("s_waitcnt lgkmcnt(" #n ")" ::: "memory")
; #define G_BAR __builtin_amdgcn_s_barrier()
; #define G_SCHED __builtin_amdgcn_sched_barrier(0)
; template <class Epi>
; __device__ __forceinline__ void gemm_phase(LAS unsigned char* lds, const bf16_t* Ag, const bf16_t* Btg, const int K, const int nM, const int nN, const Epi& E) {
;     ...
;             G_WAIT_V(6); G_BAR; G_MMA(1, 1, At, B1); G_BAR;
;             G_LDB(B0, 1, 0); G_SCHED; G_LDA(At, 1, 0); G_STAGE(G_SA(0, 1), a2 + hstep);
;             G_WAIT_L(8); G_BAR; G_WAIT_L(0); G_MMA(0, 0, At, B0); G_BAR; G_SCHED;
;             G_LDB(B1, 1, 1); G_STAGE(G_SB(1, 0), b3);
;             G_BAR; G_WAIT_L(0); G_MMA(0, 1, At, B1); G_BAR;
;             G_LDA(At, 1, 1); G_STAGE(G_SA(1, 0), a3);
;             G_BAR; G_WAIT_L(0); G_MMA(1, 0, At, B0); G_BAR; G_SCHED;
	s_setprio 1
	v_mfma_f32_16x16x32_bf16 v[60:63], v[230:233], v[156:159], v[60:63]
	v_mfma_f32_16x16x32_bf16 v[56:59], v[238:241], v[156:159], v[56:59]
	v_mfma_f32_16x16x32_bf16 v[44:47], v[230:233], v[180:183], v[44:47]
	v_mfma_f32_16x16x32_bf16 v[40:43], v[238:241], v[180:183], v[40:43]
	v_mfma_f32_16x16x32_bf16 v[28:31], v[230:233], v[188:191], v[28:31]
	v_mfma_f32_16x16x32_bf16 v[24:27], v[238:241], v[188:191], v[24:27]
	v_mfma_f32_16x16x32_bf16 v[12:15], v[230:233], v[222:225], v[12:15]
	v_mfma_f32_16x16x32_bf16 v[8:11], v[238:241], v[222:225], v[8:11]
	v_mfma_f32_16x16x32_bf16 v[60:63], v[234:237], v[160:163], v[60:63]
	v_mfma_f32_16x16x32_bf16 v[56:59], v[242:245], v[160:163], v[56:59]
	v_mfma_f32_16x16x32_bf16 v[44:47], v[234:237], v[184:187], v[44:47]
	v_mfma_f32_16x16x32_bf16 v[40:43], v[242:245], v[184:187], v[40:43]
	v_mfma_f32_16x16x32_bf16 v[28:31], v[234:237], v[192:195], v[28:31]
	v_mfma_f32_16x16x32_bf16 v[24:27], v[242:245], v[192:195], v[24:27]
	v_mfma_f32_16x16x32_bf16 v[12:15], v[234:237], v[226:229], v[12:15]
	v_mfma_f32_16x16x32_bf16 v[8:11], v[242:245], v[226:229], v[8:11]
	s_setprio 0
	s_barrier
	ds_read_b128 v[140:143], v217 offset:32768
	ds_read_b128 v[144:147], v217 offset:33792
	ds_read_b128 v[148:151], v217 offset:34816
	ds_read_b128 v[152:155], v217 offset:35840
	s_add_u32 s56, s62, 0x100000
	s_addc_u32 s57, s63, 0
	s_mov_b32 m0, s68
	ds_read_b128 v[156:159], v174 offset:32768
	ds_read_b128 v[160:163], v174 offset:33792
	ds_read_b128 v[180:183], v174 offset:34816
	ds_read_b128 v[184:187], v174 offset:35840
	ds_read_b128 v[188:191], v174 offset:36864
	ds_read_b128 v[192:195], v174 offset:37888
	ds_read_b128 v[222:225], v174 offset:38912
	global_load_lds_dwordx4 v0, s[56:57]
	s_mov_b32 m0, s69
	ds_read_b128 v[226:229], v174 offset:39936
	global_load_lds_dwordx4 v2, s[56:57]
	s_waitcnt lgkmcnt(8)
	s_barrier
	s_waitcnt lgkmcnt(0)
	s_setprio 1
	s_waitcnt lgkmcnt(0)
	v_mfma_f32_16x16x32_bf16 v[132:135], v[140:143], v[156:159], v[132:135]
	v_mfma_f32_16x16x32_bf16 v[128:131], v[148:151], v[156:159], v[128:131]
	v_mfma_f32_16x16x32_bf16 v[116:119], v[140:143], v[180:183], v[116:119]
	v_mfma_f32_16x16x32_bf16 v[112:115], v[148:151], v[180:183], v[112:115]
	v_mfma_f32_16x16x32_bf16 v[100:103], v[140:143], v[188:191], v[100:103]
	v_mfma_f32_16x16x32_bf16 v[96:99], v[148:151], v[188:191], v[96:99]
	v_mfma_f32_16x16x32_bf16 v[84:87], v[140:143], v[222:225], v[84:87]
	v_mfma_f32_16x16x32_bf16 v[80:83], v[148:151], v[222:225], v[80:83]
	v_mfma_f32_16x16x32_bf16 v[132:135], v[144:147], v[160:163], v[132:135]
	v_mfma_f32_16x16x32_bf16 v[128:131], v[152:155], v[160:163], v[128:131]
	v_mfma_f32_16x16x32_bf16 v[116:119], v[144:147], v[184:187], v[116:119]
	v_mfma_f32_16x16x32_bf16 v[112:115], v[152:155], v[184:187], v[112:115]
	v_mfma_f32_16x16x32_bf16 v[100:103], v[144:147], v[192:195], v[100:103]
	v_mfma_f32_16x16x32_bf16 v[96:99], v[152:155], v[192:195], v[96:99]
	v_mfma_f32_16x16x32_bf16 v[84:87], v[144:147], v[226:229], v[84:87]
	v_mfma_f32_16x16x32_bf16 v[80:83], v[152:155], v[226:229], v[80:83]
	s_setprio 0
	s_barrier
	s_add_i32 s26, 0, 0x1c000
	s_add_i32 m0, s65, 0x18000
	ds_read_b128 v[230:233], v217 offset:49152
	ds_read_b128 v[234:237], v217 offset:50176
	ds_read_b128 v[238:241], v217 offset:51200
	ds_read_b128 v[242:245], v217 offset:52224
	s_add_u32 s98, s60, 0x80
	s_addc_u32 s99, s61, 0
	global_load_lds_dwordx4 v0, s[98:99]
	s_add_i32 m0, s65, 0x1a000
	s_nop 0
	global_load_lds_dwordx4 v2, s[98:99]
	s_barrier
	s_waitcnt lgkmcnt(0)
	s_setprio 1
	s_waitcnt lgkmcnt(0)
	v_mfma_f32_16x16x32_bf16 v[124:127], v[230:233], v[156:159], v[124:127]
	v_mfma_f32_16x16x32_bf16 v[120:123], v[238:241], v[156:159], v[120:123]
	v_mfma_f32_16x16x32_bf16 v[108:111], v[230:233], v[180:183], v[108:111]
	v_mfma_f32_16x16x32_bf16 v[104:107], v[238:241], v[180:183], v[104:107]
	v_mfma_f32_16x16x32_bf16 v[92:95], v[230:233], v[188:191], v[92:95]
	v_mfma_f32_16x16x32_bf16 v[88:91], v[238:241], v[188:191], v[88:91]
	v_mfma_f32_16x16x32_bf16 v[76:79], v[230:233], v[222:225], v[76:79]
	v_mfma_f32_16x16x32_bf16 v[72:75], v[238:241], v[222:225], v[72:75]
	v_mfma_f32_16x16x32_bf16 v[124:127], v[234:237], v[160:163], v[124:127]
	v_mfma_f32_16x16x32_bf16 v[120:123], v[242:245], v[160:163], v[120:123]
	v_mfma_f32_16x16x32_bf16 v[108:111], v[234:237], v[184:187], v[108:111]
	v_mfma_f32_16x16x32_bf16 v[104:107], v[242:245], v[184:187], v[104:107]
	v_mfma_f32_16x16x32_bf16 v[92:95], v[234:237], v[192:195], v[92:95]
	v_mfma_f32_16x16x32_bf16 v[88:91], v[242:245], v[192:195], v[88:91]
	v_mfma_f32_16x16x32_bf16 v[76:79], v[234:237], v[226:229], v[76:79]
	v_mfma_f32_16x16x32_bf16 v[72:75], v[242:245], v[226:229], v[72:75]
	s_setprio 0
	s_mov_b32 m0, s70
	s_barrier
; #define G_STAGE(bufoff, gbase) do { _Pragma("unroll") for (int _i = 0; _i < 2; ++_i) \
;         __builtin_amdgcn_global_load_lds((const unsigned*)((const char*)(gbase) + voff[_i]), (LAS unsigned*)(lds + (bufoff) + ldsw + _i * 8192), 16, 0, 0); } while (0)
; #define G_MMA(ai, bj, At, Bt) do { __builtin_amdgcn_s_setprio(1); _Pragma("unroll") for (int m = 0; m < 4; ++m) _Pragma("unroll") for (int n = 0; n < 2; ++n) _Pragma("unroll") for (int k = 0; k < 2; ++k) \
;         acc[ai][bj][m][n] = MFMA16(Bt[n][k], At[m][k], acc[ai][bj][m][n]); __builtin_amdgcn_s_setprio(0); } while (0)
; #define G_WAIT_V(n) asm volatile("s_waitcnt vmcnt(" #n ")" ::: "memory")
; #define G_WAIT_L(n) asm volatile("s_waitcnt lgkmcnt(" #n ")" ::: "memory")
; #define G_BAR __builtin_amdgcn_s_barrier()
; #define G_SCHED __builtin_amdgcn_sched_barrier(0)
; template <class Epi>
; __device__ __forceinline__ void gemm_phase(LAS unsigned char* lds, const bf16_t* Ag, const bf16_t* Btg, const int K, const int nM, const int nN, const Epi& E) {
;     ...
;         for (int t = 0; t < nt; t += 2) {
;             const bool last = (t == nt - 2);
;             const char* a1 = cA + (size_t)(t + 1) * kstep;
;             const char* a2 = last ? nA : cA + (size_t)(t + 2) * kstep; const char* b2 = last ? nB : cB + (size_t)(t + 2) * kstep;
;             const char* a3 = a2 + kstep; const char* b3 = b2 + kstep;
;     ...
;             G_BAR; G_WAIT_L(0); G_MMA(1, 0, At, B0); G_BAR; G_SCHED;
;             G_STAGE(G_SB(1, 1), b3 + hstep);
;             G_WAIT_V(6); G_BAR; G_MMA(1, 1, At, B1); G_BAR;
	ds_read_b128 v[156:159], v174 offset:49152
	ds_read_b128 v[160:163], v174 offset:50176
	ds_read_b128 v[180:183], v174 offset:51200
	ds_read_b128 v[184:187], v174 offset:52224
	ds_read_b128 v[188:191], v174 offset:53248
	ds_read_b128 v[192:195], v174 offset:54272
	ds_read_b128 v[222:225], v174 offset:55296
	ds_read_b128 v[226:229], v174 offset:56320
	s_add_u32 s98, s62, 0x80
	s_addc_u32 s99, s63, 0
	global_load_lds_dwordx4 v0, s[98:99]
	s_mov_b32 m0, s71
	s_nop 0
	global_load_lds_dwordx4 v2, s[98:99]
	s_barrier
	s_waitcnt lgkmcnt(0)
	s_setprio 1
	s_waitcnt lgkmcnt(0)
	v_mfma_f32_16x16x32_bf16 v[68:71], v[140:143], v[156:159], v[68:71]
	v_mfma_f32_16x16x32_bf16 v[64:67], v[148:151], v[156:159], v[64:67]
	v_mfma_f32_16x16x32_bf16 v[52:55], v[140:143], v[180:183], v[52:55]
	v_mfma_f32_16x16x32_bf16 v[48:51], v[148:151], v[180:183], v[48:51]
	v_mfma_f32_16x16x32_bf16 v[36:39], v[140:143], v[188:191], v[36:39]
	v_mfma_f32_16x16x32_bf16 v[32:35], v[148:151], v[188:191], v[32:35]
	v_mfma_f32_16x16x32_bf16 v[20:23], v[140:143], v[222:225], v[20:23]
	v_mfma_f32_16x16x32_bf16 v[16:19], v[148:151], v[222:225], v[16:19]
	v_mfma_f32_16x16x32_bf16 v[68:71], v[144:147], v[160:163], v[68:71]
	v_mfma_f32_16x16x32_bf16 v[64:67], v[152:155], v[160:163], v[64:67]
	v_mfma_f32_16x16x32_bf16 v[52:55], v[144:147], v[184:187], v[52:55]
	v_mfma_f32_16x16x32_bf16 v[48:51], v[152:155], v[184:187], v[48:51]
	v_mfma_f32_16x16x32_bf16 v[36:39], v[144:147], v[192:195], v[36:39]
	v_mfma_f32_16x16x32_bf16 v[32:35], v[152:155], v[192:195], v[32:35]
	v_mfma_f32_16x16x32_bf16 v[20:23], v[144:147], v[226:229], v[20:23]
	v_mfma_f32_16x16x32_bf16 v[16:19], v[152:155], v[226:229], v[16:19]
	s_setprio 0
	s_barrier
	s_add_u32 s56, s60, 0x100080
	s_addc_u32 s57, s61, 0
	s_add_i32 s12, s26, s65
	s_add_i32 m0, s65, 0x1c000
	s_nop 0
	global_load_lds_dwordx4 v0, s[56:57]
	s_add_i32 m0, s65, 0x1e000
	s_nop 0
	global_load_lds_dwordx4 v2, s[56:57]
	s_waitcnt vmcnt(6)
	s_barrier
	s_setprio 1
	v_mfma_f32_16x16x32_bf16 v[60:63], v[230:233], v[156:159], v[60:63]
	v_mfma_f32_16x16x32_bf16 v[56:59], v[238:241], v[156:159], v[56:59]
	v_mfma_f32_16x16x32_bf16 v[44:47], v[230:233], v[180:183], v[44:47]
	v_mfma_f32_16x16x32_bf16 v[40:43], v[238:241], v[180:183], v[40:43]
	v_mfma_f32_16x16x32_bf16 v[28:31], v[230:233], v[188:191], v[28:31]
	v_mfma_f32_16x16x32_bf16 v[24:27], v[238:241], v[188:191], v[24:27]
	v_mfma_f32_16x16x32_bf16 v[12:15], v[230:233], v[222:225], v[12:15]
	v_mfma_f32_16x16x32_bf16 v[8:11], v[238:241], v[222:225], v[8:11]
	v_mfma_f32_16x16x32_bf16 v[60:63], v[234:237], v[160:163], v[60:63]
	v_mfma_f32_16x16x32_bf16 v[56:59], v[242:245], v[160:163], v[56:59]
	v_mfma_f32_16x16x32_bf16 v[44:47], v[234:237], v[184:187], v[44:47]
	v_mfma_f32_16x16x32_bf16 v[40:43], v[242:245], v[184:187], v[40:43]
	v_mfma_f32_16x16x32_bf16 v[28:31], v[234:237], v[192:195], v[28:31]
	v_mfma_f32_16x16x32_bf16 v[24:27], v[242:245], v[192:195], v[24:27]
	v_mfma_f32_16x16x32_bf16 v[12:15], v[234:237], v[226:229], v[12:15]
	v_mfma_f32_16x16x32_bf16 v[8:11], v[242:245], v[226:229], v[8:11]
	s_setprio 0
	s_add_i32 s79, s79, 2
	s_add_u32 s77, s77, 0x100
	s_addc_u32 s78, s78, 0
	s_mov_b64 s[56:57], s[58:59]
	s_cmp_gt_u32 s79, 61
	s_cbranch_scc1 .LrotX_744
	s_cmp_lg_u32 s79, 60
	s_cselect_b64 s[60:61], -1, 0
	s_add_u32 s58, s56, 0x100
	s_addc_u32 s59, s57, 0
	s_and_b64 s[60:61], s[60:61], exec
	s_cselect_b32 s63, s59, s47
	s_cselect_b32 s62, s58, s46
	s_cselect_b32 s61, s78, s15
	s_cselect_b32 s60, s77, s49
.LrotX_744:
	s_cmp_gt_u32 s79, 61
	s_barrier
	s_cbranch_scc1 .LBB0_748
	s_cmp_lg_u32 s79, 60
	s_cbranch_scc1 .LmainW_744

; #define G_STAGE(bufoff, gbase) do { _Pragma("unroll") for (int _i = 0; _i < 2; ++_i) \
;         __builtin_amdgcn_global_load_lds((const unsigned*)((const char*)(gbase) + voff[_i]), (LAS unsigned*)(lds + (bufoff) + ldsw + _i * 8192), 16, 0, 0); } while (0)
; #define G_LDA(dst, b, h) do { _Pragma("unroll") for (int m = 0; m < 4; ++m) _Pragma("unroll") for (int k = 0; k < 2; ++k) dst[m][k] = *(const LAS bf16x8*)(lds + G_SA(b, h) + aoff + m * 2048 + k * 1024); } while (0)
; #define G_LDB(dst, b, h) do { _Pragma("unroll") for (int n = 0; n < 2; ++n) _Pragma("unroll") for (int k = 0; k < 2; ++k) dst[n][k] = *(const LAS bf16x8*)(lds + G_SB(b, h) + boff + n * 2048 + k * 1024); } while (0)
; #define G_MMA(ai, bj, At, Bt) do { __builtin_amdgcn_s_setprio(1); _Pragma("unroll") for (int m = 0; m < 4; ++m) _Pragma("unroll") for (int n = 0; n < 2; ++n) _Pragma("unroll") for (int k = 0; k < 2; ++k) \
;         acc[ai][bj][m][n] = MFMA16(Bt[n][k], At[m][k], acc[ai][bj][m][n]); __builtin_amdgcn_s_setprio(0); } while (0)
; #define G_WAIT_V(n) asm volatile("s_waitcnt vmcnt(" #n ")" ::: "memory")
; #define G_WAIT_L(n) asm volatile("s_waitcnt lgkmcnt(" #n ")" ::: "memory")
; #define G_BAR __builtin_amdgcn_s_barrier()
; #define G_SCHED __builtin_amdgcn_sched_barrier(0)
; template <class Epi>
; __device__ __forceinline__ void gemm_phase(LAS unsigned char* lds, const bf16_t* Ag, const bf16_t* Btg, const int K, const int nM, const int nN, const Epi& E) {
;     ...
;             G_LDB(B0, 0, 0); G_SCHED; G_LDA(At, 0, 0); G_STAGE(G_SA(1, 1), a1 + hstep);
;             G_WAIT_L(8); G_BAR; G_WAIT_L(0); G_MMA(0, 0, At, B0); G_BAR; G_SCHED;
;             G_LDB(B1, 0, 1); G_STAGE(G_SB(0, 0), b2);
;             G_BAR; G_WAIT_L(0); G_MMA(0, 1, At, B1); G_BAR;
;             G_LDA(At, 0, 1); G_STAGE(G_SA(0, 0), a2);
;             G_BAR; G_WAIT_L(0); G_MMA(1, 0, At, B0); G_BAR; G_SCHED;
;             G_STAGE(G_SB(0, 1), b2 + hstep);
;             G_WAIT_V(6); G_BAR; G_MMA(1, 1, At, B1); G_BAR;
.LmainW_848:
	ds_read_b128 v[130:133], v217
	ds_read_b128 v[134:137], v217 offset:1024
	ds_read_b128 v[144:147], v217 offset:2048
	ds_read_b128 v[148:151], v217 offset:3072
	s_add_i32 m0, s60, 0xc000
	ds_read_b128 v[156:159], v222
	ds_read_b128 v[160:163], v222 offset:1024
	ds_read_b128 v[164:167], v222 offset:2048
	ds_read_b128 v[180:183], v222 offset:3072
	ds_read_b128 v[184:187], v222 offset:4096
	ds_read_b128 v[224:227], v222 offset:5120
	ds_read_b128 v[228:231], v222 offset:6144
	global_load_lds_dwordx4 v170, s[50:51]
	s_add_i32 m0, s60, 0xe000
	ds_read_b128 v[232:235], v222 offset:7168
	global_load_lds_dwordx4 v168, s[50:51]
	s_waitcnt lgkmcnt(8)
	s_barrier
	s_waitcnt lgkmcnt(0)
	s_setprio 1
	s_waitcnt lgkmcnt(0)
	v_mfma_f32_16x16x32_bf16 v[152:155], v[130:133], v[156:159], v[152:155]
	v_mfma_f32_16x16x32_bf16 v[138:141], v[144:147], v[156:159], v[140:143]
	v_mfma_f32_16x16x32_bf16 v[116:119], v[130:133], v[164:167], v[116:119]
	v_mfma_f32_16x16x32_bf16 v[112:115], v[144:147], v[164:167], v[112:115]
	v_mfma_f32_16x16x32_bf16 v[100:103], v[130:133], v[184:187], v[100:103]
	v_mfma_f32_16x16x32_bf16 v[96:99], v[144:147], v[184:187], v[96:99]
	v_mfma_f32_16x16x32_bf16 v[84:87], v[130:133], v[228:231], v[84:87]
	v_mfma_f32_16x16x32_bf16 v[80:83], v[144:147], v[228:231], v[80:83]
	v_mfma_f32_16x16x32_bf16 v[152:155], v[134:137], v[160:163], v[152:155]
	v_mfma_f32_16x16x32_bf16 v[138:141], v[148:151], v[160:163], v[138:141]
	v_mfma_f32_16x16x32_bf16 v[116:119], v[134:137], v[180:183], v[116:119]
	v_mfma_f32_16x16x32_bf16 v[112:115], v[148:151], v[180:183], v[112:115]
	v_mfma_f32_16x16x32_bf16 v[100:103], v[134:137], v[224:227], v[100:103]
	v_mfma_f32_16x16x32_bf16 v[96:99], v[148:151], v[224:227], v[96:99]
	v_mfma_f32_16x16x32_bf16 v[84:87], v[134:137], v[232:235], v[84:87]
	v_mfma_f32_16x16x32_bf16 v[80:83], v[148:151], v[232:235], v[80:83]
	s_setprio 0
	s_barrier
	s_add_i32 s73, 0, 0x14000
	s_add_i32 m0, s59, 0x10000
	ds_read_b128 v[236:239], v217 offset:16384
	ds_read_b128 v[240:243], v217 offset:17408
	ds_read_b128 v[244:247], v217 offset:18432
	global_load_lds_dwordx4 v0, s[52:53]
	s_add_i32 m0, s59, 0x12000
	ds_read_b128 v[248:251], v217 offset:19456
	global_load_lds_dwordx4 v2, s[52:53]
	s_barrier
	s_waitcnt lgkmcnt(0)
	s_setprio 1
	s_waitcnt lgkmcnt(0)
	v_mfma_f32_16x16x32_bf16 v[124:127], v[236:239], v[156:159], v[124:127]
	v_mfma_f32_16x16x32_bf16 v[120:123], v[244:247], v[156:159], v[120:123]
	v_mfma_f32_16x16x32_bf16 v[108:111], v[236:239], v[164:167], v[108:111]
	v_mfma_f32_16x16x32_bf16 v[104:107], v[244:247], v[164:167], v[104:107]
	v_mfma_f32_16x16x32_bf16 v[92:95], v[236:239], v[184:187], v[92:95]
	v_mfma_f32_16x16x32_bf16 v[88:91], v[244:247], v[184:187], v[88:91]
	v_mfma_f32_16x16x32_bf16 v[76:79], v[236:239], v[228:231], v[76:79]
	v_mfma_f32_16x16x32_bf16 v[72:75], v[244:247], v[228:231], v[72:75]
	v_mfma_f32_16x16x32_bf16 v[124:127], v[240:243], v[160:163], v[124:127]
	v_mfma_f32_16x16x32_bf16 v[120:123], v[248:251], v[160:163], v[120:123]
	v_mfma_f32_16x16x32_bf16 v[108:111], v[240:243], v[180:183], v[108:111]
	v_mfma_f32_16x16x32_bf16 v[104:107], v[248:251], v[180:183], v[104:107]
	v_mfma_f32_16x16x32_bf16 v[92:95], v[240:243], v[224:227], v[92:95]
	v_mfma_f32_16x16x32_bf16 v[88:91], v[248:251], v[224:227], v[88:91]
	v_mfma_f32_16x16x32_bf16 v[76:79], v[240:243], v[232:235], v[76:79]
	v_mfma_f32_16x16x32_bf16 v[72:75], v[248:251], v[232:235], v[72:75]
	s_setprio 0
	s_mov_b32 m0, s60
	s_add_u32 s76, s54, 0x80
	s_addc_u32 s77, s55, 0
	s_barrier
	ds_read_b128 v[156:159], v222 offset:16384
	ds_read_b128 v[160:163], v222 offset:17408
	ds_read_b128 v[164:167], v222 offset:18432
	ds_read_b128 v[180:183], v222 offset:19456
	ds_read_b128 v[184:187], v222 offset:20480
	ds_read_b128 v[224:227], v222 offset:21504
	ds_read_b128 v[228:231], v222 offset:22528
	ds_read_b128 v[232:235], v222 offset:23552
	global_load_lds_dwordx4 v0, s[54:55]
	s_add_u32 s76, s54, 0x80
	s_mov_b32 m0, s61
	s_addc_u32 s77, s55, 0
	global_load_lds_dwordx4 v2, s[54:55]
	s_barrier
	s_waitcnt lgkmcnt(0)
	s_setprio 1
	s_waitcnt lgkmcnt(0)
	v_mfma_f32_16x16x32_bf16 v[60:63], v[130:133], v[156:159], v[60:63]
	v_mfma_f32_16x16x32_bf16 v[56:59], v[144:147], v[156:159], v[56:59]
	v_mfma_f32_16x16x32_bf16 v[44:47], v[130:133], v[164:167], v[44:47]
	v_mfma_f32_16x16x32_bf16 v[40:43], v[144:147], v[164:167], v[40:43]
	v_mfma_f32_16x16x32_bf16 v[28:31], v[130:133], v[184:187], v[28:31]
	v_mfma_f32_16x16x32_bf16 v[24:27], v[144:147], v[184:187], v[24:27]
	v_mfma_f32_16x16x32_bf16 v[12:15], v[130:133], v[228:231], v[12:15]
	v_mfma_f32_16x16x32_bf16 v[8:11], v[144:147], v[228:231], v[8:11]
	v_mfma_f32_16x16x32_bf16 v[60:63], v[134:137], v[160:163], v[60:63]
	v_mfma_f32_16x16x32_bf16 v[56:59], v[148:151], v[160:163], v[56:59]
	v_mfma_f32_16x16x32_bf16 v[44:47], v[134:137], v[180:183], v[44:47]
	v_mfma_f32_16x16x32_bf16 v[40:43], v[148:151], v[180:183], v[40:43]
	v_mfma_f32_16x16x32_bf16 v[28:31], v[134:137], v[224:227], v[28:31]
	v_mfma_f32_16x16x32_bf16 v[24:27], v[148:151], v[224:227], v[24:27]
	v_mfma_f32_16x16x32_bf16 v[12:15], v[134:137], v[232:235], v[12:15]
	v_mfma_f32_16x16x32_bf16 v[8:11], v[148:151], v[232:235], v[8:11]
	s_setprio 0
	s_barrier
	s_add_u32 s74, s52, 0x40000
	s_addc_u32 s75, s53, 0
	s_add_i32 m0, s59, 0x14000
	s_nop 0
	global_load_lds_dwordx4 v0, s[74:75]
	s_add_i32 m0, s59, 0x16000
	s_nop 0
	global_load_lds_dwordx4 v2, s[74:75]
	s_waitcnt vmcnt(6)
	s_barrier
; #define G_STAGE(bufoff, gbase) do { _Pragma("unroll") for (int _i = 0; _i < 2; ++_i) \
;         __builtin_amdgcn_global_load_lds((const unsigned*)((const char*)(gbase) + voff[_i]), (LAS unsigned*)(lds + (bufoff) + ldsw + _i * 8192), 16, 0, 0); } while (0)
; #define G_LDA(dst, b, h) do { _Pragma("unroll") for (int m = 0; m < 4; ++m) _Pragma("unroll") for (int k = 0; k < 2; ++k) dst[m][k] = *(const LAS bf16x8*)(lds + G_SA(b, h) + aoff + m * 2048 + k * 1024); } while (0)
; #define G_LDB(dst, b, h) do { _Pragma("unroll") for (int n = 0; n < 2; ++n) _Pragma("unroll") for (int k = 0; k < 2; ++k) dst[n][k] = *(const LAS bf16x8*)(lds + G_SB(b, h) + boff + n * 2048 + k * 1024); } while (0)
; #define G_MMA(ai, bj, At, Bt) do { __builtin_amdgcn_s_setprio(1); _Pragma("unroll") for (int m = 0; m < 4; ++m) _Pragma("unroll") for (int n = 0; n < 2; ++n) _Pragma("unroll") for (int k = 0; k < 2; ++k) \
;         acc[ai][bj][m][n] = MFMA16(Bt[n][k], At[m][k], acc[ai][bj][m][n]); __builtin_amdgcn_s_setprio(0); } while (0)
; #define G_WAIT_V(n) asm volatile("s_waitcnt vmcnt(" #n ")" ::: "memory")
; #define G_WAIT_L(n) asm volatile("s_waitcnt lgkmcnt(" #n ")" ::: "memory")
; #define G_BAR __builtin_amdgcn_s_barrier()
; #define G_SCHED __builtin_amdgcn_sched_barrier(0)
; template <class Epi>
; __device__ __forceinline__ void gemm_phase(LAS unsigned char* lds, const bf16_t* Ag, const bf16_t* Btg, const int K, const int nM, const int nN, const Epi& E) {
;     ...
;             G_WAIT_V(6); G_BAR; G_MMA(1, 1, At, B1); G_BAR;
;             G_LDB(B0, 1, 0); G_SCHED; G_LDA(At, 1, 0); G_STAGE(G_SA(0, 1), a2 + hstep);
;             G_WAIT_L(8); G_BAR; G_WAIT_L(0); G_MMA(0, 0, At, B0); G_BAR; G_SCHED;
;             G_LDB(B1, 1, 1); G_STAGE(G_SB(1, 0), b3);
;             G_BAR; G_WAIT_L(0); G_MMA(0, 1, At, B1); G_BAR;
;             G_LDA(At, 1, 1); G_STAGE(G_SA(1, 0), a3);
;             G_BAR; G_WAIT_L(0); G_MMA(1, 0, At, B0); G_BAR; G_SCHED;
	s_setprio 1
	v_mfma_f32_16x16x32_bf16 v[68:71], v[236:239], v[156:159], v[68:71]
	v_mfma_f32_16x16x32_bf16 v[64:67], v[244:247], v[156:159], v[64:67]
	v_mfma_f32_16x16x32_bf16 v[52:55], v[236:239], v[164:167], v[52:55]
	v_mfma_f32_16x16x32_bf16 v[48:51], v[244:247], v[164:167], v[48:51]
	v_mfma_f32_16x16x32_bf16 v[36:39], v[236:239], v[184:187], v[36:39]
	v_mfma_f32_16x16x32_bf16 v[32:35], v[244:247], v[184:187], v[32:35]
	v_mfma_f32_16x16x32_bf16 v[20:23], v[236:239], v[228:231], v[20:23]
	v_mfma_f32_16x16x32_bf16 v[16:19], v[244:247], v[228:231], v[16:19]
	v_mfma_f32_16x16x32_bf16 v[68:71], v[240:243], v[160:163], v[68:71]
	v_mfma_f32_16x16x32_bf16 v[64:67], v[248:251], v[160:163], v[64:67]
	v_mfma_f32_16x16x32_bf16 v[52:55], v[240:243], v[180:183], v[52:55]
	v_mfma_f32_16x16x32_bf16 v[48:51], v[248:251], v[180:183], v[48:51]
	v_mfma_f32_16x16x32_bf16 v[36:39], v[240:243], v[224:227], v[36:39]
	v_mfma_f32_16x16x32_bf16 v[32:35], v[248:251], v[224:227], v[32:35]
	v_mfma_f32_16x16x32_bf16 v[20:23], v[240:243], v[232:235], v[20:23]
	v_mfma_f32_16x16x32_bf16 v[16:19], v[248:251], v[232:235], v[16:19]
	s_setprio 0
	s_barrier
	ds_read_b128 v[130:133], v217 offset:32768
	ds_read_b128 v[134:137], v217 offset:33792
	ds_read_b128 v[144:147], v217 offset:34816
	ds_read_b128 v[148:151], v217 offset:35840
	s_add_u32 s54, s54, 0x40000
	s_addc_u32 s55, s55, 0
	s_mov_b32 m0, s62
	ds_read_b128 v[156:159], v222 offset:32768
	ds_read_b128 v[160:163], v222 offset:33792
	ds_read_b128 v[164:167], v222 offset:34816
	ds_read_b128 v[180:183], v222 offset:35840
	ds_read_b128 v[184:187], v222 offset:36864
	ds_read_b128 v[224:227], v222 offset:37888
	ds_read_b128 v[228:231], v222 offset:38912
	global_load_lds_dwordx4 v0, s[54:55]
	s_mov_b32 m0, s63
	ds_read_b128 v[232:235], v222 offset:39936
	global_load_lds_dwordx4 v2, s[54:55]
	s_waitcnt lgkmcnt(8)
	s_barrier
	s_waitcnt lgkmcnt(0)
	s_setprio 1
	s_waitcnt lgkmcnt(0)
	v_mfma_f32_16x16x32_bf16 v[152:155], v[130:133], v[156:159], v[152:155]
	v_mfma_f32_16x16x32_bf16 v[138:141], v[144:147], v[156:159], v[138:141]
	v_mfma_f32_16x16x32_bf16 v[116:119], v[130:133], v[164:167], v[116:119]
	v_mfma_f32_16x16x32_bf16 v[112:115], v[144:147], v[164:167], v[112:115]
	v_mfma_f32_16x16x32_bf16 v[100:103], v[130:133], v[184:187], v[100:103]
	v_mfma_f32_16x16x32_bf16 v[96:99], v[144:147], v[184:187], v[96:99]
	v_mfma_f32_16x16x32_bf16 v[84:87], v[130:133], v[228:231], v[84:87]
	v_mfma_f32_16x16x32_bf16 v[80:83], v[144:147], v[228:231], v[80:83]
	v_mfma_f32_16x16x32_bf16 v[152:155], v[134:137], v[160:163], v[152:155]
	v_mfma_f32_16x16x32_bf16 v[140:143], v[148:151], v[160:163], v[138:141]
	v_mfma_f32_16x16x32_bf16 v[116:119], v[134:137], v[180:183], v[116:119]
	v_mfma_f32_16x16x32_bf16 v[112:115], v[148:151], v[180:183], v[112:115]
	v_mfma_f32_16x16x32_bf16 v[100:103], v[134:137], v[224:227], v[100:103]
	v_mfma_f32_16x16x32_bf16 v[96:99], v[148:151], v[224:227], v[96:99]
	v_mfma_f32_16x16x32_bf16 v[84:87], v[134:137], v[232:235], v[84:87]
	v_mfma_f32_16x16x32_bf16 v[80:83], v[148:151], v[232:235], v[80:83]
	s_setprio 0
	s_barrier
	s_add_i32 s54, 0, 0x1c000
	s_add_i32 m0, s59, 0x18000
	ds_read_b128 v[236:239], v217 offset:49152
	ds_read_b128 v[240:243], v217 offset:50176
	ds_read_b128 v[244:247], v217 offset:51200
	ds_read_b128 v[248:251], v217 offset:52224
	s_add_u32 s98, s52, 0x80
	s_addc_u32 s99, s53, 0
	global_load_lds_dwordx4 v0, s[98:99]
	s_add_i32 m0, s59, 0x1a000
	s_nop 0
	global_load_lds_dwordx4 v2, s[98:99]
	s_barrier
	s_waitcnt lgkmcnt(0)
	s_setprio 1
	s_waitcnt lgkmcnt(0)
	v_mfma_f32_16x16x32_bf16 v[124:127], v[236:239], v[156:159], v[124:127]
	v_mfma_f32_16x16x32_bf16 v[120:123], v[244:247], v[156:159], v[120:123]
	v_mfma_f32_16x16x32_bf16 v[108:111], v[236:239], v[164:167], v[108:111]
	v_mfma_f32_16x16x32_bf16 v[104:107], v[244:247], v[164:167], v[104:107]
	v_mfma_f32_16x16x32_bf16 v[92:95], v[236:239], v[184:187], v[92:95]
	v_mfma_f32_16x16x32_bf16 v[88:91], v[244:247], v[184:187], v[88:91]
	v_mfma_f32_16x16x32_bf16 v[76:79], v[236:239], v[228:231], v[76:79]
	v_mfma_f32_16x16x32_bf16 v[72:75], v[244:247], v[228:231], v[72:75]
	v_mfma_f32_16x16x32_bf16 v[124:127], v[240:243], v[160:163], v[124:127]
	v_mfma_f32_16x16x32_bf16 v[120:123], v[248:251], v[160:163], v[120:123]
	v_mfma_f32_16x16x32_bf16 v[108:111], v[240:243], v[180:183], v[108:111]
	v_mfma_f32_16x16x32_bf16 v[104:107], v[248:251], v[180:183], v[104:107]
	v_mfma_f32_16x16x32_bf16 v[92:95], v[240:243], v[224:227], v[92:95]
	v_mfma_f32_16x16x32_bf16 v[88:91], v[248:251], v[224:227], v[88:91]
	v_mfma_f32_16x16x32_bf16 v[76:79], v[240:243], v[232:235], v[76:79]
	v_mfma_f32_16x16x32_bf16 v[72:75], v[248:251], v[232:235], v[72:75]
	s_setprio 0
	s_mov_b32 m0, s64
	s_barrier
; #define G_STAGE(bufoff, gbase) do { _Pragma("unroll") for (int _i = 0; _i < 2; ++_i) \
;         __builtin_amdgcn_global_load_lds((const unsigned*)((const char*)(gbase) + voff[_i]), (LAS unsigned*)(lds + (bufoff) + ldsw + _i * 8192), 16, 0, 0); } while (0)
; #define G_MMA(ai, bj, At, Bt) do { __builtin_amdgcn_s_setprio(1); _Pragma("unroll") for (int m = 0; m < 4; ++m) _Pragma("unroll") for (int n = 0; n < 2; ++n) _Pragma("unroll") for (int k = 0; k < 2; ++k) \
;         acc[ai][bj][m][n] = MFMA16(Bt[n][k], At[m][k], acc[ai][bj][m][n]); __builtin_amdgcn_s_setprio(0); } while (0)
; #define G_WAIT_V(n) asm volatile("s_waitcnt vmcnt(" #n ")" ::: "memory")
; #define G_WAIT_L(n) asm volatile("s_waitcnt lgkmcnt(" #n ")" ::: "memory")
; #define G_BAR __builtin_amdgcn_s_barrier()
; #define G_SCHED __builtin_amdgcn_sched_barrier(0)
; template <class Epi>
; __device__ __forceinline__ void gemm_phase(LAS unsigned char* lds, const bf16_t* Ag, const bf16_t* Btg, const int K, const int nM, const int nN, const Epi& E) {
;     ...
;         for (int t = 0; t < nt; t += 2) {
;             const bool last = (t == nt - 2);
;             const char* a1 = cA + (size_t)(t + 1) * kstep;
;             const char* a2 = last ? nA : cA + (size_t)(t + 2) * kstep; const char* b2 = last ? nB : cB + (size_t)(t + 2) * kstep;
;             const char* a3 = a2 + kstep; const char* b3 = b2 + kstep;
;     ...
;             G_BAR; G_WAIT_L(0); G_MMA(1, 0, At, B0); G_BAR; G_SCHED;
;             G_STAGE(G_SB(1, 1), b3 + hstep);
;             G_WAIT_V(6); G_BAR; G_MMA(1, 1, At, B1); G_BAR;
	ds_read_b128 v[156:159], v222 offset:49152
	ds_read_b128 v[160:163], v222 offset:50176
	ds_read_b128 v[164:167], v222 offset:51200
	ds_read_b128 v[180:183], v222 offset:52224
	ds_read_b128 v[184:187], v222 offset:53248
	ds_read_b128 v[224:227], v222 offset:54272
	ds_read_b128 v[228:231], v222 offset:55296
	global_load_lds_dwordx4 v0, s[76:77]
	s_mov_b32 m0, s65
	ds_read_b128 v[232:235], v222 offset:56320
	global_load_lds_dwordx4 v2, s[76:77]
	s_barrier
	s_waitcnt lgkmcnt(0)
	s_setprio 1
	s_waitcnt lgkmcnt(0)
	v_mfma_f32_16x16x32_bf16 v[60:63], v[130:133], v[156:159], v[60:63]
	v_mfma_f32_16x16x32_bf16 v[56:59], v[144:147], v[156:159], v[56:59]
	v_mfma_f32_16x16x32_bf16 v[44:47], v[130:133], v[164:167], v[44:47]
	v_mfma_f32_16x16x32_bf16 v[40:43], v[144:147], v[164:167], v[40:43]
	v_mfma_f32_16x16x32_bf16 v[28:31], v[130:133], v[184:187], v[28:31]
	v_mfma_f32_16x16x32_bf16 v[24:27], v[144:147], v[184:187], v[24:27]
	v_mfma_f32_16x16x32_bf16 v[12:15], v[130:133], v[228:231], v[12:15]
	v_mfma_f32_16x16x32_bf16 v[8:11], v[144:147], v[228:231], v[8:11]
	v_mfma_f32_16x16x32_bf16 v[60:63], v[134:137], v[160:163], v[60:63]
	v_mfma_f32_16x16x32_bf16 v[56:59], v[148:151], v[160:163], v[56:59]
	v_mfma_f32_16x16x32_bf16 v[44:47], v[134:137], v[180:183], v[44:47]
	v_mfma_f32_16x16x32_bf16 v[40:43], v[148:151], v[180:183], v[40:43]
	v_mfma_f32_16x16x32_bf16 v[28:31], v[134:137], v[224:227], v[28:31]
	v_mfma_f32_16x16x32_bf16 v[24:27], v[148:151], v[224:227], v[24:27]
	v_mfma_f32_16x16x32_bf16 v[12:15], v[134:137], v[232:235], v[12:15]
	v_mfma_f32_16x16x32_bf16 v[8:11], v[148:151], v[232:235], v[8:11]
	s_setprio 0
	s_barrier
	s_add_u32 s52, s52, 0x40080
	s_addc_u32 s53, s53, 0
	s_add_i32 s26, s54, s59
	s_add_i32 m0, s59, 0x1c000
	s_nop 0
	global_load_lds_dwordx4 v0, s[52:53]
	s_add_i32 m0, s59, 0x1e000
	s_nop 0
	global_load_lds_dwordx4 v2, s[52:53]
	s_waitcnt vmcnt(6)
	s_barrier
	s_setprio 1
	v_mfma_f32_16x16x32_bf16 v[68:71], v[236:239], v[156:159], v[68:71]
	v_mfma_f32_16x16x32_bf16 v[64:67], v[244:247], v[156:159], v[64:67]
	v_mfma_f32_16x16x32_bf16 v[52:55], v[236:239], v[164:167], v[52:55]
	v_mfma_f32_16x16x32_bf16 v[48:51], v[244:247], v[164:167], v[48:51]
	v_mfma_f32_16x16x32_bf16 v[36:39], v[236:239], v[184:187], v[36:39]
	v_mfma_f32_16x16x32_bf16 v[32:35], v[244:247], v[184:187], v[32:35]
	v_mfma_f32_16x16x32_bf16 v[20:23], v[236:239], v[228:231], v[20:23]
	v_mfma_f32_16x16x32_bf16 v[16:19], v[244:247], v[228:231], v[16:19]
	v_mfma_f32_16x16x32_bf16 v[68:71], v[240:243], v[160:163], v[68:71]
	v_mfma_f32_16x16x32_bf16 v[64:67], v[248:251], v[160:163], v[64:67]
	v_mfma_f32_16x16x32_bf16 v[52:55], v[240:243], v[180:183], v[52:55]
	v_mfma_f32_16x16x32_bf16 v[48:51], v[248:251], v[180:183], v[48:51]
	v_mfma_f32_16x16x32_bf16 v[36:39], v[240:243], v[224:227], v[36:39]
	v_mfma_f32_16x16x32_bf16 v[32:35], v[248:251], v[224:227], v[32:35]
	v_mfma_f32_16x16x32_bf16 v[20:23], v[240:243], v[232:235], v[20:23]
	v_mfma_f32_16x16x32_bf16 v[16:19], v[248:251], v[232:235], v[16:19]
	s_setprio 0
	s_add_i32 s72, s72, 2
	s_add_u32 s70, s70, 0x100
	s_addc_u32 s71, s71, 0
	s_add_u32 s50, s50, 0x100
	s_addc_u32 s51, s51, 0
	s_cmp_gt_u32 s72, 13
	s_cbranch_scc1 .LrotX_848
	s_cmp_lg_u32 s72, 12
	s_cselect_b64 s[52:53], -1, 0
	s_add_u32 s26, s50, 0xfffc0080
	s_addc_u32 s54, s51, -1
	s_and_b64 s[52:53], s[52:53], exec
	s_cselect_b32 s55, s54, s25
	s_cselect_b32 s54, s26, s24
	s_cselect_b32 s53, s71, s14
	s_cselect_b32 s52, s70, s15
.LrotX_848:
	s_cmp_gt_u32 s72, 13
	s_barrier
	s_cbranch_scc1 .LBB0_852
	s_cmp_lg_u32 s72, 12
	s_cbranch_scc1 .LmainW_848
